# merge epilogue gate loads widened: 16-byte loads for column-group pairs, un-swapped between quarter-waves
# speedup vs baseline: 1.0280x; 1.0007x over previous
; DI f32x4 mfma16(bf16x8 a, bf16x8 b, f32x4 c) { return __builtin_amdgcn_mfma_f32_16x16x32_bf16(a, b, c, 0, 0, 0); }
; template <int NI>
; DI void gemm_kloop(f32x4 (&acc)[4][NI], const bf16_t* __restrict__ A, int lda, const bf16_t* __restrict__ B, int ldb, int K, bf16_t* sA, bf16_t* sB) {
;     ...
;   for (int kt = 0; kt < nk; ++kt) {
;     __syncthreads();
; #pragma unroll
;     for (int i = 0; i < 4; ++i) { int c = tid + 256 * i, row = c >> 3, kc = (c & 7) * 8; *(bf16x8*)(sA + row * 72 + kc) = ra[i]; }
; #pragma unroll
;     for (int i = 0; i < NB; ++i) { int c = tid + 256 * i, row = c >> 3, kc = (c & 7) * 8; *(bf16x8*)(sB + row * 72 + kc) = rb[i]; }
;     __syncthreads();
;     if (kt + 1 < nk) {
;       const int k0 = (kt + 1) * 64;
; #pragma unroll
;       for (int i = 0; i < 4; ++i) { int c = tid + 256 * i, row = c >> 3, kc = (c & 7) * 8; ra[i] = *(const bf16x8*)(A + (size_t)row * lda + k0 + kc); }
; #pragma unroll
;       for (int i = 0; i < NB; ++i) { int c = tid + 256 * i, row = c >> 3, kc = (c & 7) * 8; rb[i] = *(const bf16x8*)(B + (size_t)row * ldb + k0 + kc); }
;     }
;     __builtin_amdgcn_s_setprio(1);
; #pragma unroll
;     for (int ks = 0; ks < 2; ++ks) {
;       bf16x8 af[4];
; #pragma unroll
;       for (int mi = 0; mi < 4; ++mi) af[mi] = *(const bf16x8*)(sA + (wr * 64 + mi * 16 + lr) * 72 + ks * 32 + lq * 8);
; #pragma unroll
;       for (int nh = 0; nh < NI / 4; ++nh) {
;         bf16x8 bfr[4];
; #pragma unroll
;         for (int ni = 0; ni < 4; ++ni) bfr[ni] = *(const bf16x8*)(sB + (wc * (NI * 16) + (nh * 4 + ni) * 16 + lr) * 72 + ks * 32 + lq * 8);
; #pragma unroll
;         for (int mi = 0; mi < 4; ++mi)
; #pragma unroll
;           for (int ni = 0; ni < 4; ++ni) acc[mi][nh * 4 + ni] = mfma16(bfr[ni], af[mi], acc[mi][nh * 4 + ni]);
;       }
;     }
;     __builtin_amdgcn_s_setprio(0);
;   }
.LBB0_234:
	s_barrier
	s_waitcnt vmcnt(0)
	ds_write_b128 v147, v[30:33]
	ds_write_b128 v148, v[26:29]
	ds_write_b128 v149, v[22:25]
	ds_write_b128 v150, v[18:21]
	ds_write_b128 v147, v[14:17] offset:18432
	ds_write_b128 v148, v[10:13] offset:18432
	ds_write_b128 v149, v[6:9] offset:18432
	ds_write_b128 v150, v[2:5] offset:18432
	v_lshl_add_u64 v[2:3], v[130:131], 0, s[24:25]
	v_lshl_add_u64 v[4:5], v[132:133], 0, s[24:25]
	s_waitcnt lgkmcnt(0)
	s_barrier
	global_load_dwordx4 v[30:33], v[2:3], off
	global_load_dwordx4 v[26:29], v[4:5], off
	v_lshl_add_u64 v[2:3], v[134:135], 0, s[24:25]
	v_lshl_add_u64 v[4:5], v[136:137], 0, s[24:25]
	global_load_dwordx4 v[22:25], v[2:3], off
	global_load_dwordx4 v[18:21], v[4:5], off
	v_lshl_add_u64 v[2:3], v[138:139], 0, s[24:25]
	v_lshl_add_u64 v[4:5], v[140:141], 0, s[24:25]
	global_load_dwordx4 v[14:17], v[2:3], off
	global_load_dwordx4 v[10:13], v[4:5], off
	v_lshl_add_u64 v[2:3], v[142:143], 0, s[24:25]
	v_lshl_add_u64 v[4:5], v[144:145], 0, s[24:25]
	global_load_dwordx4 v[6:9], v[2:3], off
	s_nop 0
	global_load_dwordx4 v[2:5], v[4:5], off
	s_setprio 1
	ds_read_b128 v[152:155], v146 offset:18432
	ds_read_b128 v[156:159], v0
	ds_read_b128 v[160:163], v146 offset:20736
	ds_read_b128 v[164:167], v146 offset:23040
	ds_read_b128 v[168:171], v146 offset:25344
	s_waitcnt lgkmcnt(3)
	v_mfma_f32_16x16x32_bf16 v[38:41], v[152:155], v[156:159], v[38:41]
	s_waitcnt lgkmcnt(2)
	v_mfma_f32_16x16x32_bf16 v[82:85], v[160:163], v[156:159], v[82:85]
	s_waitcnt lgkmcnt(1)
	v_mfma_f32_16x16x32_bf16 v[78:81], v[164:167], v[156:159], v[78:81]
	s_waitcnt lgkmcnt(0)
	v_mfma_f32_16x16x32_bf16 v[74:77], v[168:171], v[156:159], v[74:77]
	ds_read_b128 v[156:159], v0 offset:2304
	s_waitcnt lgkmcnt(0)
	v_mfma_f32_16x16x32_bf16 v[70:73], v[152:155], v[156:159], v[70:73]
	v_mfma_f32_16x16x32_bf16 v[62:65], v[160:163], v[156:159], v[62:65]
	v_mfma_f32_16x16x32_bf16 v[54:57], v[164:167], v[156:159], v[54:57]
	v_mfma_f32_16x16x32_bf16 v[46:49], v[168:171], v[156:159], v[46:49]
	ds_read_b128 v[156:159], v0 offset:4608
	s_waitcnt lgkmcnt(0)
	v_mfma_f32_16x16x32_bf16 v[66:69], v[152:155], v[156:159], v[66:69]
	v_mfma_f32_16x16x32_bf16 v[58:61], v[160:163], v[156:159], v[58:61]
	v_mfma_f32_16x16x32_bf16 v[50:53], v[164:167], v[156:159], v[50:53]
	v_mfma_f32_16x16x32_bf16 v[42:45], v[168:171], v[156:159], v[42:45]
	ds_read_b128 v[156:159], v0 offset:6912
	s_waitcnt lgkmcnt(0)
	v_mfma_f32_16x16x32_bf16 v[94:97], v[152:155], v[156:159], v[94:97]
	ds_read_b128 v[152:155], v146 offset:18496
	v_mfma_f32_16x16x32_bf16 v[90:93], v[160:163], v[156:159], v[90:93]
	ds_read_b128 v[160:163], v146 offset:20800
	v_mfma_f32_16x16x32_bf16 v[86:89], v[164:167], v[156:159], v[86:89]
	ds_read_b128 v[164:167], v146 offset:23104
	v_mfma_f32_16x16x32_bf16 v[34:37], v[168:171], v[156:159], v[34:37]
	ds_read_b128 v[168:171], v146 offset:25408
	ds_read_b128 v[156:159], v0 offset:64
	s_waitcnt lgkmcnt(0)
	v_mfma_f32_16x16x32_bf16 v[38:41], v[152:155], v[156:159], v[38:41]
	v_mfma_f32_16x16x32_bf16 v[82:85], v[160:163], v[156:159], v[82:85]
	v_mfma_f32_16x16x32_bf16 v[78:81], v[164:167], v[156:159], v[78:81]
	v_mfma_f32_16x16x32_bf16 v[74:77], v[168:171], v[156:159], v[74:77]
	ds_read_b128 v[156:159], v0 offset:2368
	s_waitcnt lgkmcnt(0)
	v_mfma_f32_16x16x32_bf16 v[70:73], v[152:155], v[156:159], v[70:73]
	v_mfma_f32_16x16x32_bf16 v[62:65], v[160:163], v[156:159], v[62:65]
	v_mfma_f32_16x16x32_bf16 v[54:57], v[164:167], v[156:159], v[54:57]
	v_mfma_f32_16x16x32_bf16 v[46:49], v[168:171], v[156:159], v[46:49]
	ds_read_b128 v[156:159], v0 offset:4672
	s_waitcnt lgkmcnt(0)
	v_mfma_f32_16x16x32_bf16 v[66:69], v[152:155], v[156:159], v[66:69]
	v_mfma_f32_16x16x32_bf16 v[58:61], v[160:163], v[156:159], v[58:61]
	v_mfma_f32_16x16x32_bf16 v[50:53], v[164:167], v[156:159], v[50:53]
	v_mfma_f32_16x16x32_bf16 v[42:45], v[168:171], v[156:159], v[42:45]
	ds_read_b128 v[156:159], v0 offset:6976
	s_waitcnt lgkmcnt(0)
	v_mfma_f32_16x16x32_bf16 v[94:97], v[152:155], v[156:159], v[94:97]
	v_mfma_f32_16x16x32_bf16 v[90:93], v[160:163], v[156:159], v[90:93]
	v_mfma_f32_16x16x32_bf16 v[86:89], v[164:167], v[156:159], v[86:89]
	v_mfma_f32_16x16x32_bf16 v[34:37], v[168:171], v[156:159], v[34:37]
	s_setprio 0
	s_add_u32 s24, s24, 0x80
	s_addc_u32 s25, s25, 0
	s_cmpk_lg_i32 s24, 0x380
	s_cbranch_scc1 .LBB0_234
	s_barrier
	s_waitcnt vmcnt(7)
	ds_write_b128 v147, v[30:33]
	s_waitcnt vmcnt(6)
	ds_write_b128 v148, v[26:29]
	s_waitcnt vmcnt(5)
	ds_write_b128 v149, v[22:25]
	s_waitcnt vmcnt(4)
	ds_write_b128 v150, v[18:21]
	s_waitcnt vmcnt(3)
	ds_write_b128 v147, v[14:17] offset:18432
	s_waitcnt vmcnt(2)
	ds_write_b128 v148, v[10:13] offset:18432
	s_waitcnt vmcnt(1)
	ds_write_b128 v149, v[6:9] offset:18432
	s_waitcnt vmcnt(0)
	ds_write_b128 v150, v[2:5] offset:18432
	s_waitcnt lgkmcnt(0)
	s_barrier
; DI f32x4 mfma16(bf16x8 a, bf16x8 b, f32x4 c) { return __builtin_amdgcn_mfma_f32_16x16x32_bf16(a, b, c, 0, 0, 0); }
; template <int NI>
; DI void gemm_kloop(f32x4 (&acc)[4][NI], const bf16_t* __restrict__ A, int lda, const bf16_t* __restrict__ B, int ldb, int K, bf16_t* sA, bf16_t* sB) {
;     ...
; #pragma unroll
;     for (int ks = 0; ks < 2; ++ks) {
;       bf16x8 af[4];
; #pragma unroll
;       for (int mi = 0; mi < 4; ++mi) af[mi] = *(const bf16x8*)(sA + (wr * 64 + mi * 16 + lr) * 72 + ks * 32 + lq * 8);
; #pragma unroll
;       for (int nh = 0; nh < NI / 4; ++nh) {
;         bf16x8 bfr[4];
; #pragma unroll
;         for (int ni = 0; ni < 4; ++ni) bfr[ni] = *(const bf16x8*)(sB + (wc * (NI * 16) + (nh * 4 + ni) * 16 + lr) * 72 + ks * 32 + lq * 8);
; #pragma unroll
;         for (int mi = 0; mi < 4; ++mi)
; #pragma unroll
;           for (int ni = 0; ni < 4; ++ni) acc[mi][nh * 4 + ni] = mfma16(bfr[ni], af[mi], acc[mi][nh * 4 + ni]);
;       }
;     }
	s_setprio 1
	ds_read_b128 v[2:5], v146 offset:18432
	ds_read_b128 v[6:9], v0
	ds_read_b128 v[14:17], v146 offset:20736
	ds_read_b128 v[22:25], v146 offset:23040
	ds_read_b128 v[30:33], v146 offset:25344
	s_waitcnt lgkmcnt(3)
	v_mfma_f32_16x16x32_bf16 v[10:13], v[2:5], v[6:9], v[38:41]
	ds_read_b128 v[142:145], v146 offset:23104
	s_nop 1
	ds_read_b128 v[38:41], v0 offset:2304
	s_waitcnt lgkmcnt(4)
	v_mfma_f32_16x16x32_bf16 v[18:21], v[14:17], v[6:9], v[82:85]
	s_waitcnt lgkmcnt(3)
	v_mfma_f32_16x16x32_bf16 v[26:29], v[22:25], v[6:9], v[78:81]
	s_waitcnt lgkmcnt(2)
	v_mfma_f32_16x16x32_bf16 v[6:9], v[30:33], v[6:9], v[74:77]
	s_waitcnt lgkmcnt(0)
	v_mfma_f32_16x16x32_bf16 v[70:73], v[2:5], v[38:41], v[70:73]
	v_mfma_f32_16x16x32_bf16 v[74:77], v[14:17], v[38:41], v[62:65]
	v_mfma_f32_16x16x32_bf16 v[78:81], v[22:25], v[38:41], v[54:57]
	v_mfma_f32_16x16x32_bf16 v[82:85], v[30:33], v[38:41], v[46:49]
	ds_read_b128 v[38:41], v0 offset:4608
	s_waitcnt lgkmcnt(0)
	v_mfma_f32_16x16x32_bf16 v[66:69], v[2:5], v[38:41], v[66:69]
	v_mfma_f32_16x16x32_bf16 v[130:133], v[14:17], v[38:41], v[58:61]
	v_mfma_f32_16x16x32_bf16 v[134:137], v[22:25], v[38:41], v[50:53]
	v_mfma_f32_16x16x32_bf16 v[138:141], v[30:33], v[38:41], v[42:45]
	ds_read_b128 v[38:41], v0 offset:6912
	s_waitcnt lgkmcnt(0)
	v_mfma_f32_16x16x32_bf16 v[90:93], v[14:17], v[38:41], v[90:93]
	ds_read_b128 v[14:17], v146 offset:18496
	v_mfma_f32_16x16x32_bf16 v[86:89], v[22:25], v[38:41], v[86:89]
	ds_read_b128 v[22:25], v0 offset:64
	s_waitcnt lgkmcnt(0)
	v_mfma_f32_16x16x32_bf16 v[62:65], v[14:17], v[22:25], v[10:13]
	s_nop 2
	ds_read_b128 v[10:13], v146 offset:20800
	ds_read_b128 v[146:149], v146 offset:25408
	s_waitcnt lgkmcnt(0)
	v_mfma_f32_16x16x32_bf16 v[50:53], v[146:149], v[22:25], v[6:9]
	s_nop 2
	ds_read_b128 v[6:9], v0 offset:2368
	v_mfma_f32_16x16x32_bf16 v[2:5], v[2:5], v[38:41], v[94:97]
	v_mfma_f32_16x16x32_bf16 v[94:97], v[30:33], v[38:41], v[34:37]
	s_waitcnt lgkmcnt(0)
	v_mfma_f32_16x16x32_bf16 v[46:49], v[14:17], v[6:9], v[70:73]
	v_mfma_f32_16x16x32_bf16 v[42:45], v[10:13], v[6:9], v[74:77]
	v_mfma_f32_16x16x32_bf16 v[38:41], v[142:145], v[6:9], v[78:81]
	v_mfma_f32_16x16x32_bf16 v[34:37], v[146:149], v[6:9], v[82:85]
	ds_read_b128 v[6:9], v0 offset:4672
	s_waitcnt lgkmcnt(0)
	v_mfma_f32_16x16x32_bf16 v[30:33], v[14:17], v[6:9], v[66:69]
	s_nop 2
	ds_read_b128 v[66:69], v0 offset:6976
	v_mfma_f32_16x16x32_bf16 v[58:61], v[10:13], v[22:25], v[18:21]
	v_mfma_f32_16x16x32_bf16 v[54:57], v[142:145], v[22:25], v[26:29]
	v_mfma_f32_16x16x32_bf16 v[26:29], v[10:13], v[6:9], v[130:133]
	v_mfma_f32_16x16x32_bf16 v[22:25], v[142:145], v[6:9], v[134:137]
	v_mfma_f32_16x16x32_bf16 v[18:21], v[146:149], v[6:9], v[138:141]
	s_waitcnt lgkmcnt(0)
; DI float bflo(unsigned u) { return __uint_as_float(u << 16); }
; DI float bfhi(unsigned u) { return __uint_as_float(u & 0xffff0000u); }
; DI f32x4 mfma16(bf16x8 a, bf16x8 b, f32x4 c) { return __builtin_amdgcn_mfma_f32_16x16x32_bf16(a, b, c, 0, 0, 0); }
; DI float sigmoidf_(float x) { return 1.f / (1.f + __expf(-x)); }
; template <int NI>
; DI void gemm_kloop(f32x4 (&acc)[4][NI], const bf16_t* __restrict__ A, int lda, const bf16_t* __restrict__ B, int ldb, int K, bf16_t* sA, bf16_t* sB) {
;     ...
;         for (int mi = 0; mi < 4; ++mi)
; #pragma unroll
;           for (int ni = 0; ni < 4; ++ni) acc[mi][nh * 4 + ni] = mfma16(bfr[ni], af[mi], acc[mi][nh * 4 + ni]);
; DI void merge_item(const Params& p, int l, int item, bf16_t* lds) {
;     ...
;     EPI_LOOP({
;       u32x2 g = *(const u32x2*)(RG + (size_t)t * 3072 + br * 1024 + n0 + cl);
;       f32x4 o; o[0] = sigmoidf_(bflo(g.x)) * v[0]; o[1] = sigmoidf_(bfhi(g.x)) * v[1]; o[2] = sigmoidf_(bflo(g.y)) * v[2]; o[3] = sigmoidf_(bfhi(g.y)) * v[3];
;       if (br > 0) { u32x2 pm = mg[mi][ni]; o[0] += bflo(pm.x); o[1] += bfhi(pm.x); o[2] += bflo(pm.y); o[3] += bfhi(pm.y); }
	v_mfma_f32_16x16x32_bf16 v[14:17], v[14:17], v[66:69], v[2:5]
	v_mfma_f32_16x16x32_bf16 v[10:13], v[10:13], v[66:69], v[90:93]
	v_mfma_f32_16x16x32_bf16 v[6:9], v[142:145], v[66:69], v[86:89]
	v_mfma_f32_16x16x32_bf16 v[2:5], v[146:149], v[66:69], v[94:97]
	s_setprio 0
	v_mov_b32_e32 v0, v201
	v_mov_b32_e32 v67, v201
	s_lshl_b32 s4, s63, 11
	v_ashrrev_i32_e32 v66, 1, v67
	v_and_b32_e32 v66, 0xffffffc0, v66
	v_add_u32_e32 v66, s46, v66
	v_and_or_b32 v66, v0, 15, v66
	v_lshrrev_b32_e32 v0, 2, v0
	s_add_u32 s24, s47, s4
	v_and_b32_e32 v0, 12, v0
	s_addc_u32 s25, s48, 0
	v_and_or_b32 v0, v67, 64, v0
	v_mov_b64_e32 v[68:69], s[24:25]
	v_mad_i64_i32 v[68:69], s[4:5], v66, s8, v[68:69]
	v_lshlrev_b32_e32 v0, 1, v0
	v_lshl_add_u64 v[68:69], v[68:69], 0, v[0:1]
	v_and_b32_e32 v212, 16, v227
	v_lshrrev_b32_e32 v213, 1, v212
	v_add_u32_e32 v212, v212, v213
	v_mov_b32_e32 v213, 0
	v_lshl_add_u64 v[210:211], v[68:69], 0, v[212:213]
	global_load_dwordx4 v[172:175], v[210:211], off
	global_load_dwordx4 v[176:179], v[210:211], off offset:64
	v_or_b32_e32 v206, 16, v66
	v_mov_b64_e32 v[208:209], s[24:25]
	v_mad_i64_i32 v[208:209], s[98:99], v206, s8, v[208:209]
	v_lshl_add_u64 v[208:209], v[208:209], 0, v[0:1]
	v_lshl_add_u64 v[210:211], v[208:209], 0, v[212:213]
	global_load_dwordx4 v[180:183], v[210:211], off
	global_load_dwordx4 v[184:187], v[210:211], off offset:64
	v_or_b32_e32 v206, 32, v66
	v_mov_b64_e32 v[208:209], s[24:25]
	v_mad_i64_i32 v[208:209], s[98:99], v206, s8, v[208:209]
	v_lshl_add_u64 v[208:209], v[208:209], 0, v[0:1]
	v_lshl_add_u64 v[210:211], v[208:209], 0, v[212:213]
	global_load_dwordx4 v[188:191], v[210:211], off
	global_load_dwordx4 v[192:195], v[210:211], off offset:64
	v_or_b32_e32 v206, 48, v66
	v_mov_b64_e32 v[208:209], s[24:25]
	v_mad_i64_i32 v[208:209], s[98:99], v206, s8, v[208:209]
	v_lshl_add_u64 v[208:209], v[208:209], 0, v[0:1]
	v_lshl_add_u64 v[210:211], v[208:209], 0, v[212:213]
	global_load_dwordx4 v[196:199], v[210:211], off
	global_load_dwordx4 v[202:205], v[210:211], off offset:64
	s_cmp_lg_u32 s63, 0
	s_cselect_b64 s[26:27], -1, 0
	s_cmp_eq_u32 s63, 0
	s_waitcnt vmcnt(7)
	v_permlane16_swap_b32_e32 v172, v174
	v_permlane16_swap_b32_e32 v173, v175
	s_nop 1
	v_mov_b32_e32 v72, v172
	v_mov_b32_e32 v73, v173
	v_lshlrev_b32_e32 v67, 16, v72
	v_mul_f32_e32 v67, 0xbfb8aa3b, v67
	v_exp_f32_e32 v70, v67
	v_and_b32_e32 v67, 0xffff0000, v72
	v_mul_f32_e32 v67, 0xbfb8aa3b, v67
	v_exp_f32_e32 v71, v67
	s_nop 0
	v_pk_add_f32 v[70:71], v[70:71], 1.0 op_sel_hi:[1,0]
	s_nop 0
	v_div_scale_f32 v67, s[4:5], v71, v71, 1.0
	v_rcp_f32_e32 v72, v67
	s_nop 0
	v_fma_f32 v74, -v67, v72, 1.0
	v_fmac_f32_e32 v72, v74, v72
	v_div_scale_f32 v74, vcc, 1.0, v71, 1.0
	v_mul_f32_e32 v75, v74, v72
	v_fma_f32 v76, -v67, v75, v74
	v_fmac_f32_e32 v75, v76, v72
	v_fma_f32 v67, -v67, v75, v74
	v_div_fmas_f32 v67, v67, v72, v75
	v_div_fixup_f32 v71, v67, v71, 1.0
	v_div_scale_f32 v67, s[4:5], v70, v70, 1.0
	v_rcp_f32_e32 v72, v67
	s_nop 0
	v_fma_f32 v74, -v67, v72, 1.0
	v_fmac_f32_e32 v72, v74, v72
	v_div_scale_f32 v74, vcc, 1.0, v70, 1.0
	v_mul_f32_e32 v75, v74, v72
	v_fma_f32 v76, -v67, v75, v74
	v_fmac_f32_e32 v75, v76, v72
	v_fma_f32 v67, -v67, v75, v74
	v_div_fmas_f32 v67, v67, v72, v75
	v_div_fixup_f32 v70, v67, v70, 1.0
	v_pk_mul_f32 v[70:71], v[62:63], v[70:71]
	v_lshlrev_b32_e32 v62, 16, v73
	v_and_b32_e32 v63, 0xffff0000, v73
	v_mul_f32_e32 v62, 0xbfb8aa3b, v62
	v_mul_f32_e32 v63, 0xbfb8aa3b, v63
	v_exp_f32_e32 v62, v62
	v_exp_f32_e32 v63, v63
	s_nop 0
	v_pk_add_f32 v[62:63], v[62:63], 1.0 op_sel_hi:[1,0]
	s_nop 0
	v_div_scale_f32 v67, s[4:5], v63, v63, 1.0
	v_rcp_f32_e32 v72, v67
	s_nop 0
	v_fma_f32 v73, -v67, v72, 1.0
	v_fmac_f32_e32 v72, v73, v72
	v_div_scale_f32 v73, vcc, 1.0, v63, 1.0
	v_mul_f32_e32 v74, v73, v72
	v_fma_f32 v75, -v67, v74, v73
	v_fmac_f32_e32 v74, v75, v72
	v_fma_f32 v67, -v67, v74, v73
	v_div_fmas_f32 v67, v67, v72, v74
	v_div_fixup_f32 v63, v67, v63, 1.0
	v_div_scale_f32 v67, s[4:5], v62, v62, 1.0
	v_rcp_f32_e32 v72, v67
	s_nop 0
	v_fma_f32 v73, -v67, v72, 1.0
	v_fmac_f32_e32 v72, v73, v72
	v_div_scale_f32 v73, vcc, 1.0, v62, 1.0
	v_mul_f32_e32 v74, v73, v72
	v_fma_f32 v75, -v67, v74, v73
	v_fmac_f32_e32 v74, v75, v72
	v_fma_f32 v67, -v67, v74, v73
	v_div_fmas_f32 v67, v67, v72, v74
	v_div_fixup_f32 v62, v67, v62, 1.0
	v_pk_mul_f32 v[64:65], v[64:65], v[62:63]
	s_cbranch_scc1 .LBB0_237
	v_lshlrev_b32_e32 v62, 16, v128
	v_and_b32_e32 v63, 0xffff0000, v128
	v_pk_add_f32 v[70:71], v[70:71], v[62:63]
	v_lshlrev_b32_e32 v62, 16, v129
	v_and_b32_e32 v63, 0xffff0000, v129
	v_pk_add_f32 v[64:65], v[64:65], v[62:63]

; DI float bflo(unsigned u) { return __uint_as_float(u << 16); }
; DI float bfhi(unsigned u) { return __uint_as_float(u & 0xffff0000u); }
; DI float sigmoidf_(float x) { return 1.f / (1.f + __expf(-x)); }
; DI void merge_item(const Params& p, int l, int item, bf16_t* lds) {
;     ...
;       u32x2 g = *(const u32x2*)(RG + (size_t)t * 3072 + br * 1024 + n0 + cl);
;       f32x4 o; o[0] = sigmoidf_(bflo(g.x)) * v[0]; o[1] = sigmoidf_(bfhi(g.x)) * v[1]; o[2] = sigmoidf_(bflo(g.y)) * v[2]; o[3] = sigmoidf_(bfhi(g.y)) * v[3];
;       if (br > 0) { u32x2 pm = mg[mi][ni]; o[0] += bflo(pm.x); o[1] += bfhi(pm.x); o[2] += bflo(pm.y); o[3] += bfhi(pm.y); }
.LBB0_239:
	s_waitcnt vmcnt(7)
	v_mov_b32_e32 v64, v174
	v_mov_b32_e32 v65, v175
	v_lshlrev_b32_e32 v67, 16, v64
	v_and_b32_e32 v64, 0xffff0000, v64
	v_mul_f32_e32 v67, 0xbfb8aa3b, v67
	v_mul_f32_e32 v64, 0xbfb8aa3b, v64
	v_exp_f32_e32 v70, v67
	v_exp_f32_e32 v71, v64
	s_nop 0
	v_pk_add_f32 v[70:71], v[70:71], 1.0 op_sel_hi:[1,0]
	s_nop 0
	v_div_scale_f32 v64, s[4:5], v71, v71, 1.0
	v_rcp_f32_e32 v67, v64
	s_nop 0
	v_fma_f32 v72, -v64, v67, 1.0
	v_fmac_f32_e32 v67, v72, v67
	v_div_scale_f32 v72, vcc, 1.0, v71, 1.0
	v_mul_f32_e32 v73, v72, v67
	v_fma_f32 v74, -v64, v73, v72
	v_fmac_f32_e32 v73, v74, v67
	v_fma_f32 v64, -v64, v73, v72
	v_div_fmas_f32 v64, v64, v67, v73
	v_div_fixup_f32 v71, v64, v71, 1.0
	v_div_scale_f32 v64, s[4:5], v70, v70, 1.0
	v_rcp_f32_e32 v67, v64
	s_nop 0
	v_fma_f32 v72, -v64, v67, 1.0
	v_fmac_f32_e32 v67, v72, v67
	v_div_scale_f32 v72, vcc, 1.0, v70, 1.0
	v_mul_f32_e32 v73, v72, v67
	v_fma_f32 v74, -v64, v73, v72
	v_fmac_f32_e32 v73, v74, v67
	v_fma_f32 v64, -v64, v73, v72
	v_div_fmas_f32 v64, v64, v67, v73
	v_div_fixup_f32 v70, v64, v70, 1.0
	v_lshlrev_b32_e32 v64, 16, v65
	v_and_b32_e32 v65, 0xffff0000, v65
	v_mul_f32_e32 v64, 0xbfb8aa3b, v64
	v_mul_f32_e32 v65, 0xbfb8aa3b, v65
	v_exp_f32_e32 v64, v64
	v_exp_f32_e32 v65, v65
	v_pk_mul_f32 v[58:59], v[58:59], v[70:71]
	v_pk_add_f32 v[64:65], v[64:65], 1.0 op_sel_hi:[1,0]
	s_nop 0
	v_div_scale_f32 v67, s[4:5], v65, v65, 1.0
	v_rcp_f32_e32 v70, v67
	s_nop 0
	v_fma_f32 v71, -v67, v70, 1.0
	v_fmac_f32_e32 v70, v71, v70
	v_div_scale_f32 v71, vcc, 1.0, v65, 1.0
	v_mul_f32_e32 v72, v71, v70
	v_fma_f32 v73, -v67, v72, v71
	v_fmac_f32_e32 v72, v73, v70
	v_fma_f32 v67, -v67, v72, v71
	v_div_fmas_f32 v67, v67, v70, v72
	v_div_fixup_f32 v65, v67, v65, 1.0
	v_div_scale_f32 v67, s[4:5], v64, v64, 1.0
	v_rcp_f32_e32 v70, v67
	s_nop 0
	v_fma_f32 v71, -v67, v70, 1.0
	v_fmac_f32_e32 v70, v71, v70
	v_div_scale_f32 v71, vcc, 1.0, v64, 1.0
	v_mul_f32_e32 v72, v71, v70
	v_fma_f32 v73, -v67, v72, v71
	v_fmac_f32_e32 v72, v73, v70
	v_fma_f32 v67, -v67, v72, v71
	v_div_fmas_f32 v67, v67, v70, v72
	v_div_fixup_f32 v64, v67, v64, 1.0
	v_pk_mul_f32 v[60:61], v[60:61], v[64:65]
	v_cndmask_b32_e64 v64, 0, 1, s[26:27]
	v_cmp_ne_u32_e64 s[38:39], 1, v64
	s_andn2_b64 vcc, exec, s[26:27]
	s_cbranch_vccnz .LBB0_241
	v_lshlrev_b32_e32 v64, 16, v126
	v_and_b32_e32 v65, 0xffff0000, v126
	v_pk_add_f32 v[58:59], v[58:59], v[64:65]
	v_lshlrev_b32_e32 v64, 16, v127
	v_and_b32_e32 v65, 0xffff0000, v127
	v_pk_add_f32 v[60:61], v[60:61], v[64:65]

; DI float bflo(unsigned u) { return __uint_as_float(u << 16); }
; DI float bfhi(unsigned u) { return __uint_as_float(u & 0xffff0000u); }
; DI float sigmoidf_(float x) { return 1.f / (1.f + __expf(-x)); }
; DI void merge_item(const Params& p, int l, int item, bf16_t* lds) {
;     ...
;       u32x2 g = *(const u32x2*)(RG + (size_t)t * 3072 + br * 1024 + n0 + cl);
;       f32x4 o; o[0] = sigmoidf_(bflo(g.x)) * v[0]; o[1] = sigmoidf_(bfhi(g.x)) * v[1]; o[2] = sigmoidf_(bflo(g.y)) * v[2]; o[3] = sigmoidf_(bfhi(g.y)) * v[3];
;       if (br > 0) { u32x2 pm = mg[mi][ni]; o[0] += bflo(pm.x); o[1] += bfhi(pm.x); o[2] += bflo(pm.y); o[3] += bfhi(pm.y); }
.LBB0_243:
	s_waitcnt vmcnt(6)
	v_permlane16_swap_b32_e32 v176, v178
	v_permlane16_swap_b32_e32 v177, v179
	s_nop 1
	v_mov_b32_e32 v58, v176
	v_mov_b32_e32 v59, v177
	v_lshlrev_b32_e32 v60, 16, v58
	v_and_b32_e32 v58, 0xffff0000, v58
	v_mul_f32_e32 v60, 0xbfb8aa3b, v60
	v_mul_f32_e32 v58, 0xbfb8aa3b, v58
	v_exp_f32_e32 v60, v60
	v_exp_f32_e32 v61, v58
	s_nop 0
	v_pk_add_f32 v[60:61], v[60:61], 1.0 op_sel_hi:[1,0]
	s_nop 0
	v_div_scale_f32 v58, s[4:5], v61, v61, 1.0
	v_rcp_f32_e32 v64, v58
	s_nop 0
	v_fma_f32 v65, -v58, v64, 1.0
	v_fmac_f32_e32 v64, v65, v64
	v_div_scale_f32 v65, vcc, 1.0, v61, 1.0
	v_mul_f32_e32 v67, v65, v64
	v_fma_f32 v70, -v58, v67, v65
	v_fmac_f32_e32 v67, v70, v64
	v_fma_f32 v58, -v58, v67, v65
	v_div_fmas_f32 v58, v58, v64, v67
	v_div_fixup_f32 v61, v58, v61, 1.0
	v_div_scale_f32 v58, s[4:5], v60, v60, 1.0
	v_rcp_f32_e32 v64, v58
	s_nop 0
	v_fma_f32 v65, -v58, v64, 1.0
	v_fmac_f32_e32 v64, v65, v64
	v_div_scale_f32 v65, vcc, 1.0, v60, 1.0
	v_mul_f32_e32 v67, v65, v64
	v_fma_f32 v70, -v58, v67, v65
	v_fmac_f32_e32 v67, v70, v64
	v_fma_f32 v58, -v58, v67, v65
	v_div_fmas_f32 v58, v58, v64, v67
	v_div_fixup_f32 v60, v58, v60, 1.0
	v_lshlrev_b32_e32 v58, 16, v59
	v_and_b32_e32 v59, 0xffff0000, v59
	v_mul_f32_e32 v58, 0xbfb8aa3b, v58
	v_mul_f32_e32 v59, 0xbfb8aa3b, v59
	v_exp_f32_e32 v58, v58
	v_exp_f32_e32 v59, v59
	v_pk_mul_f32 v[54:55], v[54:55], v[60:61]
	v_pk_add_f32 v[58:59], v[58:59], 1.0 op_sel_hi:[1,0]
	s_nop 0
	v_div_scale_f32 v60, s[4:5], v59, v59, 1.0
	v_rcp_f32_e32 v61, v60
	s_nop 0
	v_fma_f32 v64, -v60, v61, 1.0
	v_fmac_f32_e32 v61, v64, v61
	v_div_scale_f32 v64, vcc, 1.0, v59, 1.0
	v_mul_f32_e32 v65, v64, v61
	v_fma_f32 v67, -v60, v65, v64
	v_fmac_f32_e32 v65, v67, v61
	v_fma_f32 v60, -v60, v65, v64
	v_div_fmas_f32 v60, v60, v61, v65
	v_div_fixup_f32 v59, v60, v59, 1.0
	v_div_scale_f32 v60, s[4:5], v58, v58, 1.0
	v_rcp_f32_e32 v61, v60
	s_nop 0
	v_fma_f32 v64, -v60, v61, 1.0
	v_fmac_f32_e32 v61, v64, v61
	v_div_scale_f32 v64, vcc, 1.0, v58, 1.0
	v_mul_f32_e32 v65, v64, v61
	v_fma_f32 v67, -v60, v65, v64
	v_fmac_f32_e32 v65, v67, v61
	v_fma_f32 v60, -v60, v65, v64
	v_div_fmas_f32 v60, v60, v61, v65
	v_div_fixup_f32 v58, v60, v58, 1.0
	v_pk_mul_f32 v[56:57], v[56:57], v[58:59]
	s_and_b64 vcc, exec, s[38:39]
	s_cbranch_vccnz .LBB0_245
	v_lshlrev_b32_e32 v58, 16, v122
	v_and_b32_e32 v59, 0xffff0000, v122
	v_pk_add_f32 v[54:55], v[54:55], v[58:59]
	v_lshlrev_b32_e32 v58, 16, v123
	v_and_b32_e32 v59, 0xffff0000, v123
	v_pk_add_f32 v[56:57], v[56:57], v[58:59]

; DI float bflo(unsigned u) { return __uint_as_float(u << 16); }
; DI float bfhi(unsigned u) { return __uint_as_float(u & 0xffff0000u); }
; DI float sigmoidf_(float x) { return 1.f / (1.f + __expf(-x)); }
; DI void merge_item(const Params& p, int l, int item, bf16_t* lds) {
;     ...
;       u32x2 g = *(const u32x2*)(RG + (size_t)t * 3072 + br * 1024 + n0 + cl);
;       f32x4 o; o[0] = sigmoidf_(bflo(g.x)) * v[0]; o[1] = sigmoidf_(bfhi(g.x)) * v[1]; o[2] = sigmoidf_(bflo(g.y)) * v[2]; o[3] = sigmoidf_(bfhi(g.y)) * v[3];
;       if (br > 0) { u32x2 pm = mg[mi][ni]; o[0] += bflo(pm.x); o[1] += bfhi(pm.x); o[2] += bflo(pm.y); o[3] += bfhi(pm.y); }
.LBB0_247:
	s_waitcnt vmcnt(6)
	v_mov_b32_e32 v54, v178
	v_mov_b32_e32 v55, v179
	v_lshlrev_b32_e32 v56, 16, v54
	v_and_b32_e32 v54, 0xffff0000, v54
	v_mul_f32_e32 v56, 0xbfb8aa3b, v56
	v_mul_f32_e32 v54, 0xbfb8aa3b, v54
	v_exp_f32_e32 v56, v56
	v_exp_f32_e32 v57, v54
	s_nop 0
	v_pk_add_f32 v[56:57], v[56:57], 1.0 op_sel_hi:[1,0]
	s_nop 0
	v_div_scale_f32 v54, s[4:5], v57, v57, 1.0
	v_rcp_f32_e32 v58, v54
	s_nop 0
	v_fma_f32 v59, -v54, v58, 1.0
	v_fmac_f32_e32 v58, v59, v58
	v_div_scale_f32 v59, vcc, 1.0, v57, 1.0
	v_mul_f32_e32 v60, v59, v58
	v_fma_f32 v61, -v54, v60, v59
	v_fmac_f32_e32 v60, v61, v58
	v_fma_f32 v54, -v54, v60, v59
	v_div_fmas_f32 v54, v54, v58, v60
	v_div_fixup_f32 v57, v54, v57, 1.0
	v_div_scale_f32 v54, s[4:5], v56, v56, 1.0
	v_rcp_f32_e32 v58, v54
	s_nop 0
	v_fma_f32 v59, -v54, v58, 1.0
	v_fmac_f32_e32 v58, v59, v58
	v_div_scale_f32 v59, vcc, 1.0, v56, 1.0
	v_mul_f32_e32 v60, v59, v58
	v_fma_f32 v61, -v54, v60, v59
	v_fmac_f32_e32 v60, v61, v58
	v_fma_f32 v54, -v54, v60, v59
	v_div_fmas_f32 v54, v54, v58, v60
	v_div_fixup_f32 v56, v54, v56, 1.0
	v_lshlrev_b32_e32 v54, 16, v55
	v_and_b32_e32 v55, 0xffff0000, v55
	v_mul_f32_e32 v54, 0xbfb8aa3b, v54
	v_mul_f32_e32 v55, 0xbfb8aa3b, v55
	v_exp_f32_e32 v54, v54
	v_exp_f32_e32 v55, v55
	v_pk_mul_f32 v[50:51], v[50:51], v[56:57]
	v_pk_add_f32 v[54:55], v[54:55], 1.0 op_sel_hi:[1,0]
	s_nop 0
	v_div_scale_f32 v56, s[4:5], v55, v55, 1.0
	v_rcp_f32_e32 v57, v56
	s_nop 0
	v_fma_f32 v58, -v56, v57, 1.0
	v_fmac_f32_e32 v57, v58, v57
	v_div_scale_f32 v58, vcc, 1.0, v55, 1.0
	v_mul_f32_e32 v59, v58, v57
	v_fma_f32 v60, -v56, v59, v58
	v_fmac_f32_e32 v59, v60, v57
	v_fma_f32 v56, -v56, v59, v58
	v_div_fmas_f32 v56, v56, v57, v59
	v_div_fixup_f32 v55, v56, v55, 1.0
	v_div_scale_f32 v56, s[4:5], v54, v54, 1.0
	v_rcp_f32_e32 v57, v56
	s_nop 0
	v_fma_f32 v58, -v56, v57, 1.0
	v_fmac_f32_e32 v57, v58, v57
	v_div_scale_f32 v58, vcc, 1.0, v54, 1.0
	v_mul_f32_e32 v59, v58, v57
	v_fma_f32 v60, -v56, v59, v58
	v_fmac_f32_e32 v59, v60, v57
	v_fma_f32 v56, -v56, v59, v58
	v_div_fmas_f32 v56, v56, v57, v59
	v_div_fixup_f32 v54, v56, v54, 1.0
	v_pk_mul_f32 v[52:53], v[52:53], v[54:55]
	s_and_b64 vcc, exec, s[38:39]
	s_cbranch_vccnz .LBB0_249
	v_lshlrev_b32_e32 v54, 16, v120
	v_and_b32_e32 v55, 0xffff0000, v120
	v_pk_add_f32 v[50:51], v[50:51], v[54:55]
	v_lshlrev_b32_e32 v54, 16, v121
	v_and_b32_e32 v55, 0xffff0000, v121
	v_pk_add_f32 v[52:53], v[52:53], v[54:55]

; DI float bflo(unsigned u) { return __uint_as_float(u << 16); }
; DI float bfhi(unsigned u) { return __uint_as_float(u & 0xffff0000u); }
; DI float sigmoidf_(float x) { return 1.f / (1.f + __expf(-x)); }
; DI void merge_item(const Params& p, int l, int item, bf16_t* lds) {
;     ...
;       u32x2 g = *(const u32x2*)(RG + (size_t)t * 3072 + br * 1024 + n0 + cl);
;       f32x4 o; o[0] = sigmoidf_(bflo(g.x)) * v[0]; o[1] = sigmoidf_(bfhi(g.x)) * v[1]; o[2] = sigmoidf_(bflo(g.y)) * v[2]; o[3] = sigmoidf_(bfhi(g.y)) * v[3];
;       if (br > 0) { u32x2 pm = mg[mi][ni]; o[0] += bflo(pm.x); o[1] += bfhi(pm.x); o[2] += bflo(pm.y); o[3] += bfhi(pm.y); }
.LBB0_251:
	v_or_b32_e32 v52, 16, v66
	v_mov_b64_e32 v[50:51], s[24:25]
	v_mad_i64_i32 v[50:51], s[4:5], v52, s8, v[50:51]
	v_lshl_add_u64 v[50:51], v[50:51], 0, v[0:1]
	s_waitcnt vmcnt(5)
	v_permlane16_swap_b32_e32 v180, v182
	v_permlane16_swap_b32_e32 v181, v183
	s_nop 1
	v_mov_b32_e32 v56, v180
	v_mov_b32_e32 v57, v181
	v_lshlrev_b32_e32 v53, 16, v56
	v_mul_f32_e32 v53, 0xbfb8aa3b, v53
	v_exp_f32_e32 v54, v53
	v_and_b32_e32 v53, 0xffff0000, v56
	v_mul_f32_e32 v53, 0xbfb8aa3b, v53
	v_exp_f32_e32 v55, v53
	s_nop 0
	v_pk_add_f32 v[54:55], v[54:55], 1.0 op_sel_hi:[1,0]
	s_nop 0
	v_div_scale_f32 v53, s[4:5], v55, v55, 1.0
	v_rcp_f32_e32 v56, v53
	s_nop 0
	v_fma_f32 v58, -v53, v56, 1.0
	v_fmac_f32_e32 v56, v58, v56
	v_div_scale_f32 v58, vcc, 1.0, v55, 1.0
	v_mul_f32_e32 v59, v58, v56
	v_fma_f32 v60, -v53, v59, v58
	v_fmac_f32_e32 v59, v60, v56
	v_fma_f32 v53, -v53, v59, v58
	v_div_fmas_f32 v53, v53, v56, v59
	v_div_fixup_f32 v55, v53, v55, 1.0
	v_div_scale_f32 v53, s[4:5], v54, v54, 1.0
	v_rcp_f32_e32 v56, v53
	s_nop 0
	v_fma_f32 v58, -v53, v56, 1.0
	v_fmac_f32_e32 v56, v58, v56
	v_div_scale_f32 v58, vcc, 1.0, v54, 1.0
	v_mul_f32_e32 v59, v58, v56
	v_fma_f32 v60, -v53, v59, v58
	v_fmac_f32_e32 v59, v60, v56
	v_fma_f32 v53, -v53, v59, v58
	v_div_fmas_f32 v53, v53, v56, v59
	v_div_fixup_f32 v54, v53, v54, 1.0
	v_pk_mul_f32 v[54:55], v[46:47], v[54:55]
	v_lshlrev_b32_e32 v46, 16, v57
	v_and_b32_e32 v47, 0xffff0000, v57
	v_mul_f32_e32 v46, 0xbfb8aa3b, v46
	v_mul_f32_e32 v47, 0xbfb8aa3b, v47
	v_exp_f32_e32 v46, v46
	v_exp_f32_e32 v47, v47
	s_nop 0
	v_pk_add_f32 v[46:47], v[46:47], 1.0 op_sel_hi:[1,0]
	s_nop 0
	v_div_scale_f32 v53, s[4:5], v47, v47, 1.0
	v_rcp_f32_e32 v56, v53
	s_nop 0
	v_fma_f32 v57, -v53, v56, 1.0
	v_fmac_f32_e32 v56, v57, v56
	v_div_scale_f32 v57, vcc, 1.0, v47, 1.0
	v_mul_f32_e32 v58, v57, v56
	v_fma_f32 v59, -v53, v58, v57
	v_fmac_f32_e32 v58, v59, v56
	v_fma_f32 v53, -v53, v58, v57
	v_div_fmas_f32 v53, v53, v56, v58
	v_div_fixup_f32 v47, v53, v47, 1.0
	v_div_scale_f32 v53, s[4:5], v46, v46, 1.0
	v_rcp_f32_e32 v56, v53
	s_nop 0
	v_fma_f32 v57, -v53, v56, 1.0
	v_fmac_f32_e32 v56, v57, v56
	v_div_scale_f32 v57, vcc, 1.0, v46, 1.0
	v_mul_f32_e32 v58, v57, v56
	v_fma_f32 v59, -v53, v58, v57
	v_fmac_f32_e32 v58, v59, v56
	v_fma_f32 v53, -v53, v58, v57
	v_div_fmas_f32 v53, v53, v56, v58
	v_div_fixup_f32 v46, v53, v46, 1.0
	v_pk_mul_f32 v[48:49], v[48:49], v[46:47]
	s_and_b64 vcc, exec, s[38:39]
	s_cbranch_vccnz .LBB0_253
	v_lshlrev_b32_e32 v46, 16, v124
	v_and_b32_e32 v47, 0xffff0000, v124
	v_pk_add_f32 v[54:55], v[54:55], v[46:47]
	v_lshlrev_b32_e32 v46, 16, v125
	v_and_b32_e32 v47, 0xffff0000, v125
	v_pk_add_f32 v[48:49], v[48:49], v[46:47]

; DI float bflo(unsigned u) { return __uint_as_float(u << 16); }
; DI float bfhi(unsigned u) { return __uint_as_float(u & 0xffff0000u); }
; DI float sigmoidf_(float x) { return 1.f / (1.f + __expf(-x)); }
; DI void merge_item(const Params& p, int l, int item, bf16_t* lds) {
;     ...
;       u32x2 g = *(const u32x2*)(RG + (size_t)t * 3072 + br * 1024 + n0 + cl);
;       f32x4 o; o[0] = sigmoidf_(bflo(g.x)) * v[0]; o[1] = sigmoidf_(bfhi(g.x)) * v[1]; o[2] = sigmoidf_(bflo(g.y)) * v[2]; o[3] = sigmoidf_(bfhi(g.y)) * v[3];
;       if (br > 0) { u32x2 pm = mg[mi][ni]; o[0] += bflo(pm.x); o[1] += bfhi(pm.x); o[2] += bflo(pm.y); o[3] += bfhi(pm.y); }
.LBB0_255:
	s_waitcnt vmcnt(5)
	v_mov_b32_e32 v48, v182
	v_mov_b32_e32 v49, v183
	v_lshlrev_b32_e32 v52, 16, v48
	v_and_b32_e32 v48, 0xffff0000, v48
	v_mul_f32_e32 v52, 0xbfb8aa3b, v52
	v_mul_f32_e32 v48, 0xbfb8aa3b, v48
	v_exp_f32_e32 v52, v52
	v_exp_f32_e32 v53, v48
	s_nop 0
	v_pk_add_f32 v[52:53], v[52:53], 1.0 op_sel_hi:[1,0]
	s_nop 0
	v_div_scale_f32 v48, s[4:5], v53, v53, 1.0
	v_rcp_f32_e32 v54, v48
	s_nop 0
	v_fma_f32 v55, -v48, v54, 1.0
	v_fmac_f32_e32 v54, v55, v54
	v_div_scale_f32 v55, vcc, 1.0, v53, 1.0
	v_mul_f32_e32 v56, v55, v54
	v_fma_f32 v57, -v48, v56, v55
	v_fmac_f32_e32 v56, v57, v54
	v_fma_f32 v48, -v48, v56, v55
	v_div_fmas_f32 v48, v48, v54, v56
	v_div_fixup_f32 v53, v48, v53, 1.0
	v_div_scale_f32 v48, s[4:5], v52, v52, 1.0
	v_rcp_f32_e32 v54, v48
	s_nop 0
	v_fma_f32 v55, -v48, v54, 1.0
	v_fmac_f32_e32 v54, v55, v54
	v_div_scale_f32 v55, vcc, 1.0, v52, 1.0
	v_mul_f32_e32 v56, v55, v54
	v_fma_f32 v57, -v48, v56, v55
	v_fmac_f32_e32 v56, v57, v54
	v_fma_f32 v48, -v48, v56, v55
	v_div_fmas_f32 v48, v48, v54, v56
	v_div_fixup_f32 v52, v48, v52, 1.0
	v_lshlrev_b32_e32 v48, 16, v49
	v_and_b32_e32 v49, 0xffff0000, v49
	v_mul_f32_e32 v48, 0xbfb8aa3b, v48
	v_mul_f32_e32 v49, 0xbfb8aa3b, v49
	v_exp_f32_e32 v48, v48
	v_exp_f32_e32 v49, v49
	v_pk_mul_f32 v[42:43], v[42:43], v[52:53]
	v_pk_add_f32 v[48:49], v[48:49], 1.0 op_sel_hi:[1,0]
	s_nop 0
	v_div_scale_f32 v52, s[4:5], v49, v49, 1.0
	v_rcp_f32_e32 v53, v52
	s_nop 0
	v_fma_f32 v54, -v52, v53, 1.0
	v_fmac_f32_e32 v53, v54, v53
	v_div_scale_f32 v54, vcc, 1.0, v49, 1.0
	v_mul_f32_e32 v55, v54, v53
	v_fma_f32 v56, -v52, v55, v54
	v_fmac_f32_e32 v55, v56, v53
	v_fma_f32 v52, -v52, v55, v54
	v_div_fmas_f32 v52, v52, v53, v55
	v_div_fixup_f32 v49, v52, v49, 1.0
	v_div_scale_f32 v52, s[4:5], v48, v48, 1.0
	v_rcp_f32_e32 v53, v52
	s_nop 0
	v_fma_f32 v54, -v52, v53, 1.0
	v_fmac_f32_e32 v53, v54, v53
	v_div_scale_f32 v54, vcc, 1.0, v48, 1.0
	v_mul_f32_e32 v55, v54, v53
	v_fma_f32 v56, -v52, v55, v54
	v_fmac_f32_e32 v55, v56, v53
	v_fma_f32 v52, -v52, v55, v54
	v_div_fmas_f32 v52, v52, v53, v55
	v_div_fixup_f32 v48, v52, v48, 1.0
	v_pk_mul_f32 v[44:45], v[44:45], v[48:49]
	s_and_b64 vcc, exec, s[38:39]
	s_cbranch_vccnz .LBB0_257
	v_lshlrev_b32_e32 v48, 16, v118
	v_and_b32_e32 v49, 0xffff0000, v118
	v_pk_add_f32 v[42:43], v[42:43], v[48:49]
	v_lshlrev_b32_e32 v48, 16, v119
	v_and_b32_e32 v49, 0xffff0000, v119
	v_pk_add_f32 v[44:45], v[44:45], v[48:49]

; DI float bflo(unsigned u) { return __uint_as_float(u << 16); }
; DI float bfhi(unsigned u) { return __uint_as_float(u & 0xffff0000u); }
; DI float sigmoidf_(float x) { return 1.f / (1.f + __expf(-x)); }
; DI void merge_item(const Params& p, int l, int item, bf16_t* lds) {
;     ...
;       u32x2 g = *(const u32x2*)(RG + (size_t)t * 3072 + br * 1024 + n0 + cl);
;       f32x4 o; o[0] = sigmoidf_(bflo(g.x)) * v[0]; o[1] = sigmoidf_(bfhi(g.x)) * v[1]; o[2] = sigmoidf_(bflo(g.y)) * v[2]; o[3] = sigmoidf_(bfhi(g.y)) * v[3];
;       if (br > 0) { u32x2 pm = mg[mi][ni]; o[0] += bflo(pm.x); o[1] += bfhi(pm.x); o[2] += bflo(pm.y); o[3] += bfhi(pm.y); }
.LBB0_259:
	s_waitcnt vmcnt(4)
	v_permlane16_swap_b32_e32 v184, v186
	v_permlane16_swap_b32_e32 v185, v187
	s_nop 1
	v_mov_b32_e32 v42, v184
	v_mov_b32_e32 v43, v185
	v_lshlrev_b32_e32 v44, 16, v42
	v_and_b32_e32 v42, 0xffff0000, v42
	v_mul_f32_e32 v44, 0xbfb8aa3b, v44
	v_mul_f32_e32 v42, 0xbfb8aa3b, v42
	v_exp_f32_e32 v44, v44
	v_exp_f32_e32 v45, v42
	s_nop 0
	v_pk_add_f32 v[44:45], v[44:45], 1.0 op_sel_hi:[1,0]
	s_nop 0
	v_div_scale_f32 v42, s[4:5], v45, v45, 1.0
	v_rcp_f32_e32 v48, v42
	s_nop 0
	v_fma_f32 v49, -v42, v48, 1.0
	v_fmac_f32_e32 v48, v49, v48
	v_div_scale_f32 v49, vcc, 1.0, v45, 1.0
	v_mul_f32_e32 v52, v49, v48
	v_fma_f32 v53, -v42, v52, v49
	v_fmac_f32_e32 v52, v53, v48
	v_fma_f32 v42, -v42, v52, v49
	v_div_fmas_f32 v42, v42, v48, v52
	v_div_fixup_f32 v45, v42, v45, 1.0
	v_div_scale_f32 v42, s[4:5], v44, v44, 1.0
	v_rcp_f32_e32 v48, v42
	s_nop 0
	v_fma_f32 v49, -v42, v48, 1.0
	v_fmac_f32_e32 v48, v49, v48
	v_div_scale_f32 v49, vcc, 1.0, v44, 1.0
	v_mul_f32_e32 v52, v49, v48
	v_fma_f32 v53, -v42, v52, v49
	v_fmac_f32_e32 v52, v53, v48
	v_fma_f32 v42, -v42, v52, v49
	v_div_fmas_f32 v42, v42, v48, v52
	v_div_fixup_f32 v44, v42, v44, 1.0
	v_lshlrev_b32_e32 v42, 16, v43
	v_and_b32_e32 v43, 0xffff0000, v43
	v_mul_f32_e32 v42, 0xbfb8aa3b, v42
	v_mul_f32_e32 v43, 0xbfb8aa3b, v43
	v_exp_f32_e32 v42, v42
	v_exp_f32_e32 v43, v43
	v_pk_mul_f32 v[38:39], v[38:39], v[44:45]
	v_pk_add_f32 v[42:43], v[42:43], 1.0 op_sel_hi:[1,0]
	s_nop 0
	v_div_scale_f32 v44, s[4:5], v43, v43, 1.0
	v_rcp_f32_e32 v45, v44
	s_nop 0
	v_fma_f32 v48, -v44, v45, 1.0
	v_fmac_f32_e32 v45, v48, v45
	v_div_scale_f32 v48, vcc, 1.0, v43, 1.0
	v_mul_f32_e32 v49, v48, v45
	v_fma_f32 v52, -v44, v49, v48
	v_fmac_f32_e32 v49, v52, v45
	v_fma_f32 v44, -v44, v49, v48
	v_div_fmas_f32 v44, v44, v45, v49
	v_div_fixup_f32 v43, v44, v43, 1.0
	v_div_scale_f32 v44, s[4:5], v42, v42, 1.0
	v_rcp_f32_e32 v45, v44
	s_nop 0
	v_fma_f32 v48, -v44, v45, 1.0
	v_fmac_f32_e32 v45, v48, v45
	v_div_scale_f32 v48, vcc, 1.0, v42, 1.0
	v_mul_f32_e32 v49, v48, v45
	v_fma_f32 v52, -v44, v49, v48
	v_fmac_f32_e32 v49, v52, v45
	v_fma_f32 v44, -v44, v49, v48
	v_div_fmas_f32 v44, v44, v45, v49
	v_div_fixup_f32 v42, v44, v42, 1.0
	v_pk_mul_f32 v[40:41], v[40:41], v[42:43]
	s_and_b64 vcc, exec, s[38:39]
	s_cbranch_vccnz .LBB0_261
	v_lshlrev_b32_e32 v42, 16, v114
	v_and_b32_e32 v43, 0xffff0000, v114
	v_pk_add_f32 v[38:39], v[38:39], v[42:43]
	v_lshlrev_b32_e32 v42, 16, v115
	v_and_b32_e32 v43, 0xffff0000, v115
	v_pk_add_f32 v[40:41], v[40:41], v[42:43]

; DI float bflo(unsigned u) { return __uint_as_float(u << 16); }
; DI float bfhi(unsigned u) { return __uint_as_float(u & 0xffff0000u); }
; DI float sigmoidf_(float x) { return 1.f / (1.f + __expf(-x)); }
; DI void merge_item(const Params& p, int l, int item, bf16_t* lds) {
;     ...
;       u32x2 g = *(const u32x2*)(RG + (size_t)t * 3072 + br * 1024 + n0 + cl);
;       f32x4 o; o[0] = sigmoidf_(bflo(g.x)) * v[0]; o[1] = sigmoidf_(bfhi(g.x)) * v[1]; o[2] = sigmoidf_(bflo(g.y)) * v[2]; o[3] = sigmoidf_(bfhi(g.y)) * v[3];
;       if (br > 0) { u32x2 pm = mg[mi][ni]; o[0] += bflo(pm.x); o[1] += bfhi(pm.x); o[2] += bflo(pm.y); o[3] += bfhi(pm.y); }
.LBB0_263:
	s_waitcnt vmcnt(4)
	v_mov_b32_e32 v38, v186
	v_mov_b32_e32 v39, v187
	v_lshlrev_b32_e32 v40, 16, v38
	v_and_b32_e32 v38, 0xffff0000, v38
	v_mul_f32_e32 v40, 0xbfb8aa3b, v40
	v_mul_f32_e32 v38, 0xbfb8aa3b, v38
	v_exp_f32_e32 v40, v40
	v_exp_f32_e32 v41, v38
	s_nop 0
	v_pk_add_f32 v[40:41], v[40:41], 1.0 op_sel_hi:[1,0]
	s_nop 0
	v_div_scale_f32 v38, s[4:5], v41, v41, 1.0
	v_rcp_f32_e32 v42, v38
	s_nop 0
	v_fma_f32 v43, -v38, v42, 1.0
	v_fmac_f32_e32 v42, v43, v42
	v_div_scale_f32 v43, vcc, 1.0, v41, 1.0
	v_mul_f32_e32 v44, v43, v42
	v_fma_f32 v45, -v38, v44, v43
	v_fmac_f32_e32 v44, v45, v42
	v_fma_f32 v38, -v38, v44, v43
	v_div_fmas_f32 v38, v38, v42, v44
	v_div_fixup_f32 v41, v38, v41, 1.0
	v_div_scale_f32 v38, s[4:5], v40, v40, 1.0
	v_rcp_f32_e32 v42, v38
	s_nop 0
	v_fma_f32 v43, -v38, v42, 1.0
	v_fmac_f32_e32 v42, v43, v42
	v_div_scale_f32 v43, vcc, 1.0, v40, 1.0
	v_mul_f32_e32 v44, v43, v42
	v_fma_f32 v45, -v38, v44, v43
	v_fmac_f32_e32 v44, v45, v42
	v_fma_f32 v38, -v38, v44, v43
	v_div_fmas_f32 v38, v38, v42, v44
	v_div_fixup_f32 v40, v38, v40, 1.0
	v_lshlrev_b32_e32 v38, 16, v39
	v_and_b32_e32 v39, 0xffff0000, v39
	v_mul_f32_e32 v38, 0xbfb8aa3b, v38
	v_mul_f32_e32 v39, 0xbfb8aa3b, v39
	v_exp_f32_e32 v38, v38
	v_exp_f32_e32 v39, v39
	v_pk_mul_f32 v[34:35], v[34:35], v[40:41]
	v_pk_add_f32 v[38:39], v[38:39], 1.0 op_sel_hi:[1,0]
	s_nop 0
	v_div_scale_f32 v40, s[4:5], v39, v39, 1.0
	v_rcp_f32_e32 v41, v40
	s_nop 0
	v_fma_f32 v42, -v40, v41, 1.0
	v_fmac_f32_e32 v41, v42, v41
	v_div_scale_f32 v42, vcc, 1.0, v39, 1.0
	v_mul_f32_e32 v43, v42, v41
	v_fma_f32 v44, -v40, v43, v42
	v_fmac_f32_e32 v43, v44, v41
	v_fma_f32 v40, -v40, v43, v42
	v_div_fmas_f32 v40, v40, v41, v43
	v_div_fixup_f32 v39, v40, v39, 1.0
	v_div_scale_f32 v40, s[4:5], v38, v38, 1.0
	v_rcp_f32_e32 v41, v40
	s_nop 0
	v_fma_f32 v42, -v40, v41, 1.0
	v_fmac_f32_e32 v41, v42, v41
	v_div_scale_f32 v42, vcc, 1.0, v38, 1.0
	v_mul_f32_e32 v43, v42, v41
	v_fma_f32 v44, -v40, v43, v42
	v_fmac_f32_e32 v43, v44, v41
	v_fma_f32 v40, -v40, v43, v42
	v_div_fmas_f32 v40, v40, v41, v43
	v_div_fixup_f32 v38, v40, v38, 1.0
	v_pk_mul_f32 v[36:37], v[36:37], v[38:39]
	s_and_b64 vcc, exec, s[38:39]
	s_cbranch_vccnz .LBB0_265
	v_lshlrev_b32_e32 v38, 16, v112
	v_and_b32_e32 v39, 0xffff0000, v112
	v_pk_add_f32 v[34:35], v[34:35], v[38:39]
	v_lshlrev_b32_e32 v38, 16, v113
	v_and_b32_e32 v39, 0xffff0000, v113
	v_pk_add_f32 v[36:37], v[36:37], v[38:39]

; DI float bflo(unsigned u) { return __uint_as_float(u << 16); }
; DI float bfhi(unsigned u) { return __uint_as_float(u & 0xffff0000u); }
; DI float sigmoidf_(float x) { return 1.f / (1.f + __expf(-x)); }
; DI void merge_item(const Params& p, int l, int item, bf16_t* lds) {
;     ...
;       u32x2 g = *(const u32x2*)(RG + (size_t)t * 3072 + br * 1024 + n0 + cl);
;       f32x4 o; o[0] = sigmoidf_(bflo(g.x)) * v[0]; o[1] = sigmoidf_(bfhi(g.x)) * v[1]; o[2] = sigmoidf_(bflo(g.y)) * v[2]; o[3] = sigmoidf_(bfhi(g.y)) * v[3];
;       if (br > 0) { u32x2 pm = mg[mi][ni]; o[0] += bflo(pm.x); o[1] += bfhi(pm.x); o[2] += bflo(pm.y); o[3] += bfhi(pm.y); }
.LBB0_267:
	v_or_b32_e32 v36, 32, v66
	v_mov_b64_e32 v[34:35], s[24:25]
	v_mad_i64_i32 v[34:35], s[4:5], v36, s8, v[34:35]
	v_lshl_add_u64 v[34:35], v[34:35], 0, v[0:1]
	s_waitcnt vmcnt(3)
	v_permlane16_swap_b32_e32 v188, v190
	v_permlane16_swap_b32_e32 v189, v191
	s_nop 1
	v_mov_b32_e32 v40, v188
	v_mov_b32_e32 v41, v189
	v_lshlrev_b32_e32 v37, 16, v40
	v_mul_f32_e32 v37, 0xbfb8aa3b, v37
	v_exp_f32_e32 v38, v37
	v_and_b32_e32 v37, 0xffff0000, v40
	v_mul_f32_e32 v37, 0xbfb8aa3b, v37
	v_exp_f32_e32 v39, v37
	s_nop 0
	v_pk_add_f32 v[38:39], v[38:39], 1.0 op_sel_hi:[1,0]
	s_nop 0
	v_div_scale_f32 v37, s[4:5], v39, v39, 1.0
	v_rcp_f32_e32 v40, v37
	s_nop 0
	v_fma_f32 v42, -v37, v40, 1.0
	v_fmac_f32_e32 v40, v42, v40
	v_div_scale_f32 v42, vcc, 1.0, v39, 1.0
	v_mul_f32_e32 v43, v42, v40
	v_fma_f32 v44, -v37, v43, v42
	v_fmac_f32_e32 v43, v44, v40
	v_fma_f32 v37, -v37, v43, v42
	v_div_fmas_f32 v37, v37, v40, v43
	v_div_fixup_f32 v39, v37, v39, 1.0
	v_div_scale_f32 v37, s[4:5], v38, v38, 1.0
	v_rcp_f32_e32 v40, v37
	s_nop 0
	v_fma_f32 v42, -v37, v40, 1.0
	v_fmac_f32_e32 v40, v42, v40
	v_div_scale_f32 v42, vcc, 1.0, v38, 1.0
	v_mul_f32_e32 v43, v42, v40
	v_fma_f32 v44, -v37, v43, v42
	v_fmac_f32_e32 v43, v44, v40
	v_fma_f32 v37, -v37, v43, v42
	v_div_fmas_f32 v37, v37, v40, v43
	v_div_fixup_f32 v38, v37, v38, 1.0
	v_pk_mul_f32 v[38:39], v[30:31], v[38:39]
	v_lshlrev_b32_e32 v30, 16, v41
	v_and_b32_e32 v31, 0xffff0000, v41
	v_mul_f32_e32 v30, 0xbfb8aa3b, v30
	v_mul_f32_e32 v31, 0xbfb8aa3b, v31
	v_exp_f32_e32 v30, v30
	v_exp_f32_e32 v31, v31
	s_nop 0
	v_pk_add_f32 v[30:31], v[30:31], 1.0 op_sel_hi:[1,0]
	s_nop 0
	v_div_scale_f32 v37, s[4:5], v31, v31, 1.0
	v_rcp_f32_e32 v40, v37
	s_nop 0
	v_fma_f32 v41, -v37, v40, 1.0
	v_fmac_f32_e32 v40, v41, v40
	v_div_scale_f32 v41, vcc, 1.0, v31, 1.0
	v_mul_f32_e32 v42, v41, v40
	v_fma_f32 v43, -v37, v42, v41
	v_fmac_f32_e32 v42, v43, v40
	v_fma_f32 v37, -v37, v42, v41
	v_div_fmas_f32 v37, v37, v40, v42
	v_div_fixup_f32 v31, v37, v31, 1.0
	v_div_scale_f32 v37, s[4:5], v30, v30, 1.0
	v_rcp_f32_e32 v40, v37
	s_nop 0
	v_fma_f32 v41, -v37, v40, 1.0
	v_fmac_f32_e32 v40, v41, v40
	v_div_scale_f32 v41, vcc, 1.0, v30, 1.0
	v_mul_f32_e32 v42, v41, v40
	v_fma_f32 v43, -v37, v42, v41
	v_fmac_f32_e32 v42, v43, v40
	v_fma_f32 v37, -v37, v42, v41
	v_div_fmas_f32 v37, v37, v40, v42
	v_div_fixup_f32 v30, v37, v30, 1.0
	v_pk_mul_f32 v[32:33], v[32:33], v[30:31]
	s_and_b64 vcc, exec, s[38:39]
	s_cbranch_vccnz .LBB0_269
	v_lshlrev_b32_e32 v30, 16, v116
	v_and_b32_e32 v31, 0xffff0000, v116
	v_pk_add_f32 v[38:39], v[38:39], v[30:31]
	v_lshlrev_b32_e32 v30, 16, v117
	v_and_b32_e32 v31, 0xffff0000, v117
	v_pk_add_f32 v[32:33], v[32:33], v[30:31]

; DI float bflo(unsigned u) { return __uint_as_float(u << 16); }
; DI float bfhi(unsigned u) { return __uint_as_float(u & 0xffff0000u); }
; DI float sigmoidf_(float x) { return 1.f / (1.f + __expf(-x)); }
; DI void merge_item(const Params& p, int l, int item, bf16_t* lds) {
;     ...
;       u32x2 g = *(const u32x2*)(RG + (size_t)t * 3072 + br * 1024 + n0 + cl);
;       f32x4 o; o[0] = sigmoidf_(bflo(g.x)) * v[0]; o[1] = sigmoidf_(bfhi(g.x)) * v[1]; o[2] = sigmoidf_(bflo(g.y)) * v[2]; o[3] = sigmoidf_(bfhi(g.y)) * v[3];
;       if (br > 0) { u32x2 pm = mg[mi][ni]; o[0] += bflo(pm.x); o[1] += bfhi(pm.x); o[2] += bflo(pm.y); o[3] += bfhi(pm.y); }
.LBB0_271:
	s_waitcnt vmcnt(3)
	v_mov_b32_e32 v32, v190
	v_mov_b32_e32 v33, v191
	v_lshlrev_b32_e32 v36, 16, v32
	v_and_b32_e32 v32, 0xffff0000, v32
	v_mul_f32_e32 v36, 0xbfb8aa3b, v36
	v_mul_f32_e32 v32, 0xbfb8aa3b, v32
	v_exp_f32_e32 v36, v36
	v_exp_f32_e32 v37, v32
	s_nop 0
	v_pk_add_f32 v[36:37], v[36:37], 1.0 op_sel_hi:[1,0]
	s_nop 0
	v_div_scale_f32 v32, s[4:5], v37, v37, 1.0
	v_rcp_f32_e32 v38, v32
	s_nop 0
	v_fma_f32 v39, -v32, v38, 1.0
	v_fmac_f32_e32 v38, v39, v38
	v_div_scale_f32 v39, vcc, 1.0, v37, 1.0
	v_mul_f32_e32 v40, v39, v38
	v_fma_f32 v41, -v32, v40, v39
	v_fmac_f32_e32 v40, v41, v38
	v_fma_f32 v32, -v32, v40, v39
	v_div_fmas_f32 v32, v32, v38, v40
	v_div_fixup_f32 v37, v32, v37, 1.0
	v_div_scale_f32 v32, s[4:5], v36, v36, 1.0
	v_rcp_f32_e32 v38, v32
	s_nop 0
	v_fma_f32 v39, -v32, v38, 1.0
	v_fmac_f32_e32 v38, v39, v38
	v_div_scale_f32 v39, vcc, 1.0, v36, 1.0
	v_mul_f32_e32 v40, v39, v38
	v_fma_f32 v41, -v32, v40, v39
	v_fmac_f32_e32 v40, v41, v38
	v_fma_f32 v32, -v32, v40, v39
	v_div_fmas_f32 v32, v32, v38, v40
	v_div_fixup_f32 v36, v32, v36, 1.0
	v_lshlrev_b32_e32 v32, 16, v33
	v_and_b32_e32 v33, 0xffff0000, v33
	v_mul_f32_e32 v32, 0xbfb8aa3b, v32
	v_mul_f32_e32 v33, 0xbfb8aa3b, v33
	v_exp_f32_e32 v32, v32
	v_exp_f32_e32 v33, v33
	v_pk_mul_f32 v[26:27], v[26:27], v[36:37]
	v_pk_add_f32 v[32:33], v[32:33], 1.0 op_sel_hi:[1,0]
	s_nop 0
	v_div_scale_f32 v36, s[4:5], v33, v33, 1.0
	v_rcp_f32_e32 v37, v36
	s_nop 0
	v_fma_f32 v38, -v36, v37, 1.0
	v_fmac_f32_e32 v37, v38, v37
	v_div_scale_f32 v38, vcc, 1.0, v33, 1.0
	v_mul_f32_e32 v39, v38, v37
	v_fma_f32 v40, -v36, v39, v38
	v_fmac_f32_e32 v39, v40, v37
	v_fma_f32 v36, -v36, v39, v38
	v_div_fmas_f32 v36, v36, v37, v39
	v_div_fixup_f32 v33, v36, v33, 1.0
	v_div_scale_f32 v36, s[4:5], v32, v32, 1.0
	v_rcp_f32_e32 v37, v36
	s_nop 0
	v_fma_f32 v38, -v36, v37, 1.0
	v_fmac_f32_e32 v37, v38, v37
	v_div_scale_f32 v38, vcc, 1.0, v32, 1.0
	v_mul_f32_e32 v39, v38, v37
	v_fma_f32 v40, -v36, v39, v38
	v_fmac_f32_e32 v39, v40, v37
	v_fma_f32 v36, -v36, v39, v38
	v_div_fmas_f32 v36, v36, v37, v39
	v_div_fixup_f32 v32, v36, v32, 1.0
	v_pk_mul_f32 v[28:29], v[28:29], v[32:33]
	s_and_b64 vcc, exec, s[38:39]
	s_cbranch_vccnz .LBB0_273
	v_lshlrev_b32_e32 v32, 16, v110
	v_and_b32_e32 v33, 0xffff0000, v110
	v_pk_add_f32 v[26:27], v[26:27], v[32:33]
	v_lshlrev_b32_e32 v32, 16, v111
	v_and_b32_e32 v33, 0xffff0000, v111
	v_pk_add_f32 v[28:29], v[28:29], v[32:33]

; DI float bflo(unsigned u) { return __uint_as_float(u << 16); }
; DI float bfhi(unsigned u) { return __uint_as_float(u & 0xffff0000u); }
; DI float sigmoidf_(float x) { return 1.f / (1.f + __expf(-x)); }
; DI void merge_item(const Params& p, int l, int item, bf16_t* lds) {
;     ...
;       u32x2 g = *(const u32x2*)(RG + (size_t)t * 3072 + br * 1024 + n0 + cl);
;       f32x4 o; o[0] = sigmoidf_(bflo(g.x)) * v[0]; o[1] = sigmoidf_(bfhi(g.x)) * v[1]; o[2] = sigmoidf_(bflo(g.y)) * v[2]; o[3] = sigmoidf_(bfhi(g.y)) * v[3];
;       if (br > 0) { u32x2 pm = mg[mi][ni]; o[0] += bflo(pm.x); o[1] += bfhi(pm.x); o[2] += bflo(pm.y); o[3] += bfhi(pm.y); }
.LBB0_275:
	s_waitcnt vmcnt(2)
	v_permlane16_swap_b32_e32 v192, v194
	v_permlane16_swap_b32_e32 v193, v195
	s_nop 1
	v_mov_b32_e32 v26, v192
	v_mov_b32_e32 v27, v193
	v_lshlrev_b32_e32 v28, 16, v26
	v_and_b32_e32 v26, 0xffff0000, v26
	v_mul_f32_e32 v28, 0xbfb8aa3b, v28
	v_mul_f32_e32 v26, 0xbfb8aa3b, v26
	v_exp_f32_e32 v28, v28
	v_exp_f32_e32 v29, v26
	s_nop 0
	v_pk_add_f32 v[28:29], v[28:29], 1.0 op_sel_hi:[1,0]
	s_nop 0
	v_div_scale_f32 v26, s[4:5], v29, v29, 1.0
	v_rcp_f32_e32 v32, v26
	s_nop 0
	v_fma_f32 v33, -v26, v32, 1.0
	v_fmac_f32_e32 v32, v33, v32
	v_div_scale_f32 v33, vcc, 1.0, v29, 1.0
	v_mul_f32_e32 v36, v33, v32
	v_fma_f32 v37, -v26, v36, v33
	v_fmac_f32_e32 v36, v37, v32
	v_fma_f32 v26, -v26, v36, v33
	v_div_fmas_f32 v26, v26, v32, v36
	v_div_fixup_f32 v29, v26, v29, 1.0
	v_div_scale_f32 v26, s[4:5], v28, v28, 1.0
	v_rcp_f32_e32 v32, v26
	s_nop 0
	v_fma_f32 v33, -v26, v32, 1.0
	v_fmac_f32_e32 v32, v33, v32
	v_div_scale_f32 v33, vcc, 1.0, v28, 1.0
	v_mul_f32_e32 v36, v33, v32
	v_fma_f32 v37, -v26, v36, v33
	v_fmac_f32_e32 v36, v37, v32
	v_fma_f32 v26, -v26, v36, v33
	v_div_fmas_f32 v26, v26, v32, v36
	v_div_fixup_f32 v28, v26, v28, 1.0
	v_lshlrev_b32_e32 v26, 16, v27
	v_and_b32_e32 v27, 0xffff0000, v27
	v_mul_f32_e32 v26, 0xbfb8aa3b, v26
	v_mul_f32_e32 v27, 0xbfb8aa3b, v27
	v_exp_f32_e32 v26, v26
	v_exp_f32_e32 v27, v27
	v_pk_mul_f32 v[22:23], v[22:23], v[28:29]
	v_pk_add_f32 v[26:27], v[26:27], 1.0 op_sel_hi:[1,0]
	s_nop 0
	v_div_scale_f32 v28, s[4:5], v27, v27, 1.0
	v_rcp_f32_e32 v29, v28
	s_nop 0
	v_fma_f32 v32, -v28, v29, 1.0
	v_fmac_f32_e32 v29, v32, v29
	v_div_scale_f32 v32, vcc, 1.0, v27, 1.0
	v_mul_f32_e32 v33, v32, v29
	v_fma_f32 v36, -v28, v33, v32
	v_fmac_f32_e32 v33, v36, v29
	v_fma_f32 v28, -v28, v33, v32
	v_div_fmas_f32 v28, v28, v29, v33
	v_div_fixup_f32 v27, v28, v27, 1.0
	v_div_scale_f32 v28, s[4:5], v26, v26, 1.0
	v_rcp_f32_e32 v29, v28
	s_nop 0
	v_fma_f32 v32, -v28, v29, 1.0
	v_fmac_f32_e32 v29, v32, v29
	v_div_scale_f32 v32, vcc, 1.0, v26, 1.0
	v_mul_f32_e32 v33, v32, v29
	v_fma_f32 v36, -v28, v33, v32
	v_fmac_f32_e32 v33, v36, v29
	v_fma_f32 v28, -v28, v33, v32
	v_div_fmas_f32 v28, v28, v29, v33
	v_div_fixup_f32 v26, v28, v26, 1.0
	v_pk_mul_f32 v[24:25], v[24:25], v[26:27]
	s_and_b64 vcc, exec, s[38:39]
	s_cbranch_vccnz .LBB0_277
	v_lshlrev_b32_e32 v26, 16, v106
	v_and_b32_e32 v27, 0xffff0000, v106
	v_pk_add_f32 v[22:23], v[22:23], v[26:27]
	v_lshlrev_b32_e32 v26, 16, v107
	v_and_b32_e32 v27, 0xffff0000, v107
	v_pk_add_f32 v[24:25], v[24:25], v[26:27]

; DI float bflo(unsigned u) { return __uint_as_float(u << 16); }
; DI float bfhi(unsigned u) { return __uint_as_float(u & 0xffff0000u); }
; DI float sigmoidf_(float x) { return 1.f / (1.f + __expf(-x)); }
; DI void merge_item(const Params& p, int l, int item, bf16_t* lds) {
;     ...
;       u32x2 g = *(const u32x2*)(RG + (size_t)t * 3072 + br * 1024 + n0 + cl);
;       f32x4 o; o[0] = sigmoidf_(bflo(g.x)) * v[0]; o[1] = sigmoidf_(bfhi(g.x)) * v[1]; o[2] = sigmoidf_(bflo(g.y)) * v[2]; o[3] = sigmoidf_(bfhi(g.y)) * v[3];
;       if (br > 0) { u32x2 pm = mg[mi][ni]; o[0] += bflo(pm.x); o[1] += bfhi(pm.x); o[2] += bflo(pm.y); o[3] += bfhi(pm.y); }
.LBB0_279:
	s_waitcnt vmcnt(2)
	v_mov_b32_e32 v22, v194
	v_mov_b32_e32 v23, v195
	v_lshlrev_b32_e32 v24, 16, v22
	v_and_b32_e32 v22, 0xffff0000, v22
	v_mul_f32_e32 v24, 0xbfb8aa3b, v24
	v_mul_f32_e32 v22, 0xbfb8aa3b, v22
	v_exp_f32_e32 v24, v24
	v_exp_f32_e32 v25, v22
	s_nop 0
	v_pk_add_f32 v[24:25], v[24:25], 1.0 op_sel_hi:[1,0]
	s_nop 0
	v_div_scale_f32 v22, s[4:5], v25, v25, 1.0
	v_rcp_f32_e32 v26, v22
	s_nop 0
	v_fma_f32 v27, -v22, v26, 1.0
	v_fmac_f32_e32 v26, v27, v26
	v_div_scale_f32 v27, vcc, 1.0, v25, 1.0
	v_mul_f32_e32 v28, v27, v26
	v_fma_f32 v29, -v22, v28, v27
	v_fmac_f32_e32 v28, v29, v26
	v_fma_f32 v22, -v22, v28, v27
	v_div_fmas_f32 v22, v22, v26, v28
	v_div_fixup_f32 v25, v22, v25, 1.0
	v_div_scale_f32 v22, s[4:5], v24, v24, 1.0
	v_rcp_f32_e32 v26, v22
	s_nop 0
	v_fma_f32 v27, -v22, v26, 1.0
	v_fmac_f32_e32 v26, v27, v26
	v_div_scale_f32 v27, vcc, 1.0, v24, 1.0
	v_mul_f32_e32 v28, v27, v26
	v_fma_f32 v29, -v22, v28, v27
	v_fmac_f32_e32 v28, v29, v26
	v_fma_f32 v22, -v22, v28, v27
	v_div_fmas_f32 v22, v22, v26, v28
	v_div_fixup_f32 v24, v22, v24, 1.0
	v_lshlrev_b32_e32 v22, 16, v23
	v_and_b32_e32 v23, 0xffff0000, v23
	v_mul_f32_e32 v22, 0xbfb8aa3b, v22
	v_mul_f32_e32 v23, 0xbfb8aa3b, v23
	v_exp_f32_e32 v22, v22
	v_exp_f32_e32 v23, v23
	v_pk_mul_f32 v[18:19], v[18:19], v[24:25]
	v_pk_add_f32 v[22:23], v[22:23], 1.0 op_sel_hi:[1,0]
	s_nop 0
	v_div_scale_f32 v24, s[4:5], v23, v23, 1.0
	v_rcp_f32_e32 v25, v24
	s_nop 0
	v_fma_f32 v26, -v24, v25, 1.0
	v_fmac_f32_e32 v25, v26, v25
	v_div_scale_f32 v26, vcc, 1.0, v23, 1.0
	v_mul_f32_e32 v27, v26, v25
	v_fma_f32 v28, -v24, v27, v26
	v_fmac_f32_e32 v27, v28, v25
	v_fma_f32 v24, -v24, v27, v26
	v_div_fmas_f32 v24, v24, v25, v27
	v_div_fixup_f32 v23, v24, v23, 1.0
	v_div_scale_f32 v24, s[4:5], v22, v22, 1.0
	v_rcp_f32_e32 v25, v24
	s_nop 0
	v_fma_f32 v26, -v24, v25, 1.0
	v_fmac_f32_e32 v25, v26, v25
	v_div_scale_f32 v26, vcc, 1.0, v22, 1.0
	v_mul_f32_e32 v27, v26, v25
	v_fma_f32 v28, -v24, v27, v26
	v_fmac_f32_e32 v27, v28, v25
	v_fma_f32 v24, -v24, v27, v26
	v_div_fmas_f32 v24, v24, v25, v27
	v_div_fixup_f32 v22, v24, v22, 1.0
	v_pk_mul_f32 v[20:21], v[20:21], v[22:23]
	s_and_b64 vcc, exec, s[38:39]
	s_cbranch_vccnz .LBB0_281
	v_lshlrev_b32_e32 v22, 16, v104
	v_and_b32_e32 v23, 0xffff0000, v104
	v_pk_add_f32 v[18:19], v[18:19], v[22:23]
	v_lshlrev_b32_e32 v22, 16, v105
	v_and_b32_e32 v23, 0xffff0000, v105
	v_pk_add_f32 v[20:21], v[20:21], v[22:23]

; DI float bflo(unsigned u) { return __uint_as_float(u << 16); }
; DI float bfhi(unsigned u) { return __uint_as_float(u & 0xffff0000u); }
; DI float sigmoidf_(float x) { return 1.f / (1.f + __expf(-x)); }
; DI void merge_item(const Params& p, int l, int item, bf16_t* lds) {
;     ...
;       u32x2 g = *(const u32x2*)(RG + (size_t)t * 3072 + br * 1024 + n0 + cl);
;       f32x4 o; o[0] = sigmoidf_(bflo(g.x)) * v[0]; o[1] = sigmoidf_(bfhi(g.x)) * v[1]; o[2] = sigmoidf_(bflo(g.y)) * v[2]; o[3] = sigmoidf_(bfhi(g.y)) * v[3];
;       if (br > 0) { u32x2 pm = mg[mi][ni]; o[0] += bflo(pm.x); o[1] += bfhi(pm.x); o[2] += bflo(pm.y); o[3] += bfhi(pm.y); }
.LBB0_283:
	v_or_b32_e32 v20, 48, v66
	v_mov_b64_e32 v[18:19], s[24:25]
	v_mad_i64_i32 v[18:19], s[4:5], v20, s8, v[18:19]
	v_lshl_add_u64 v[18:19], v[18:19], 0, v[0:1]
	s_waitcnt vmcnt(1)
	v_permlane16_swap_b32_e32 v196, v198
	v_permlane16_swap_b32_e32 v197, v199
	s_nop 1
	v_mov_b32_e32 v24, v196
	v_mov_b32_e32 v25, v197
	v_lshlrev_b32_e32 v21, 16, v24
	v_mul_f32_e32 v21, 0xbfb8aa3b, v21
	v_exp_f32_e32 v22, v21
	v_and_b32_e32 v21, 0xffff0000, v24
	v_mul_f32_e32 v21, 0xbfb8aa3b, v21
	v_exp_f32_e32 v23, v21
	s_nop 0
	v_pk_add_f32 v[22:23], v[22:23], 1.0 op_sel_hi:[1,0]
	s_nop 0
	v_div_scale_f32 v21, s[4:5], v23, v23, 1.0
	v_rcp_f32_e32 v24, v21
	s_nop 0
	v_fma_f32 v26, -v21, v24, 1.0
	v_fmac_f32_e32 v24, v26, v24
	v_div_scale_f32 v26, vcc, 1.0, v23, 1.0
	v_mul_f32_e32 v27, v26, v24
	v_fma_f32 v28, -v21, v27, v26
	v_fmac_f32_e32 v27, v28, v24
	v_fma_f32 v21, -v21, v27, v26
	v_div_fmas_f32 v21, v21, v24, v27
	v_div_fixup_f32 v23, v21, v23, 1.0
	v_div_scale_f32 v21, s[4:5], v22, v22, 1.0
	v_rcp_f32_e32 v24, v21
	s_nop 0
	v_fma_f32 v26, -v21, v24, 1.0
	v_fmac_f32_e32 v24, v26, v24
	v_div_scale_f32 v26, vcc, 1.0, v22, 1.0
	v_mul_f32_e32 v27, v26, v24
	v_fma_f32 v28, -v21, v27, v26
	v_fmac_f32_e32 v27, v28, v24
	v_fma_f32 v21, -v21, v27, v26
	v_div_fmas_f32 v21, v21, v24, v27
	v_div_fixup_f32 v22, v21, v22, 1.0
	v_pk_mul_f32 v[22:23], v[14:15], v[22:23]
	v_lshlrev_b32_e32 v14, 16, v25
	v_and_b32_e32 v15, 0xffff0000, v25
	v_mul_f32_e32 v14, 0xbfb8aa3b, v14
	v_mul_f32_e32 v15, 0xbfb8aa3b, v15
	v_exp_f32_e32 v14, v14
	v_exp_f32_e32 v15, v15
	s_nop 0
	v_pk_add_f32 v[14:15], v[14:15], 1.0 op_sel_hi:[1,0]
	s_nop 0
	v_div_scale_f32 v21, s[4:5], v15, v15, 1.0
	v_rcp_f32_e32 v24, v21
	s_nop 0
	v_fma_f32 v25, -v21, v24, 1.0
	v_fmac_f32_e32 v24, v25, v24
	v_div_scale_f32 v25, vcc, 1.0, v15, 1.0
	v_mul_f32_e32 v26, v25, v24
	v_fma_f32 v27, -v21, v26, v25
	v_fmac_f32_e32 v26, v27, v24
	v_fma_f32 v21, -v21, v26, v25
	v_div_fmas_f32 v21, v21, v24, v26
	v_div_fixup_f32 v15, v21, v15, 1.0
	v_div_scale_f32 v21, s[4:5], v14, v14, 1.0
	v_rcp_f32_e32 v24, v21
	s_nop 0
	v_fma_f32 v25, -v21, v24, 1.0
	v_fmac_f32_e32 v24, v25, v24
	v_div_scale_f32 v25, vcc, 1.0, v14, 1.0
	v_mul_f32_e32 v26, v25, v24
	v_fma_f32 v27, -v21, v26, v25
	v_fmac_f32_e32 v26, v27, v24
	v_fma_f32 v21, -v21, v26, v25
	v_div_fmas_f32 v21, v21, v24, v26
	v_div_fixup_f32 v14, v21, v14, 1.0
	v_pk_mul_f32 v[16:17], v[16:17], v[14:15]
	s_and_b64 vcc, exec, s[38:39]
	s_cbranch_vccnz .LBB0_285
	v_lshlrev_b32_e32 v14, 16, v108
	v_and_b32_e32 v15, 0xffff0000, v108
	v_pk_add_f32 v[22:23], v[22:23], v[14:15]
	v_lshlrev_b32_e32 v14, 16, v109
	v_and_b32_e32 v15, 0xffff0000, v109
	v_pk_add_f32 v[16:17], v[16:17], v[14:15]

; DI float bflo(unsigned u) { return __uint_as_float(u << 16); }
; DI float bfhi(unsigned u) { return __uint_as_float(u & 0xffff0000u); }
; DI float sigmoidf_(float x) { return 1.f / (1.f + __expf(-x)); }
; DI void merge_item(const Params& p, int l, int item, bf16_t* lds) {
;     ...
;       u32x2 g = *(const u32x2*)(RG + (size_t)t * 3072 + br * 1024 + n0 + cl);
;       f32x4 o; o[0] = sigmoidf_(bflo(g.x)) * v[0]; o[1] = sigmoidf_(bfhi(g.x)) * v[1]; o[2] = sigmoidf_(bflo(g.y)) * v[2]; o[3] = sigmoidf_(bfhi(g.y)) * v[3];
;       if (br > 0) { u32x2 pm = mg[mi][ni]; o[0] += bflo(pm.x); o[1] += bfhi(pm.x); o[2] += bflo(pm.y); o[3] += bfhi(pm.y); }
.LBB0_287:
	s_waitcnt vmcnt(1)
	v_mov_b32_e32 v16, v198
	v_mov_b32_e32 v17, v199
	v_lshlrev_b32_e32 v20, 16, v16
	v_and_b32_e32 v16, 0xffff0000, v16
	v_mul_f32_e32 v20, 0xbfb8aa3b, v20
	v_mul_f32_e32 v16, 0xbfb8aa3b, v16
	v_exp_f32_e32 v20, v20
	v_exp_f32_e32 v21, v16
	s_nop 0
	v_pk_add_f32 v[20:21], v[20:21], 1.0 op_sel_hi:[1,0]
	s_nop 0
	v_div_scale_f32 v16, s[4:5], v21, v21, 1.0
	v_rcp_f32_e32 v22, v16
	s_nop 0
	v_fma_f32 v23, -v16, v22, 1.0
	v_fmac_f32_e32 v22, v23, v22
	v_div_scale_f32 v23, vcc, 1.0, v21, 1.0
	v_mul_f32_e32 v24, v23, v22
	v_fma_f32 v25, -v16, v24, v23
	v_fmac_f32_e32 v24, v25, v22
	v_fma_f32 v16, -v16, v24, v23
	v_div_fmas_f32 v16, v16, v22, v24
	v_div_fixup_f32 v21, v16, v21, 1.0
	v_div_scale_f32 v16, s[4:5], v20, v20, 1.0
	v_rcp_f32_e32 v22, v16
	s_nop 0
	v_fma_f32 v23, -v16, v22, 1.0
	v_fmac_f32_e32 v22, v23, v22
	v_div_scale_f32 v23, vcc, 1.0, v20, 1.0
	v_mul_f32_e32 v24, v23, v22
	v_fma_f32 v25, -v16, v24, v23
	v_fmac_f32_e32 v24, v25, v22
	v_fma_f32 v16, -v16, v24, v23
	v_div_fmas_f32 v16, v16, v22, v24
	v_div_fixup_f32 v20, v16, v20, 1.0
	v_lshlrev_b32_e32 v16, 16, v17
	v_and_b32_e32 v17, 0xffff0000, v17
	v_mul_f32_e32 v16, 0xbfb8aa3b, v16
	v_mul_f32_e32 v17, 0xbfb8aa3b, v17
	v_exp_f32_e32 v16, v16
	v_exp_f32_e32 v17, v17
	v_pk_mul_f32 v[10:11], v[10:11], v[20:21]
	v_pk_add_f32 v[16:17], v[16:17], 1.0 op_sel_hi:[1,0]
	s_nop 0
	v_div_scale_f32 v20, s[4:5], v17, v17, 1.0
	v_rcp_f32_e32 v21, v20
	s_nop 0
	v_fma_f32 v22, -v20, v21, 1.0
	v_fmac_f32_e32 v21, v22, v21
	v_div_scale_f32 v22, vcc, 1.0, v17, 1.0
	v_mul_f32_e32 v23, v22, v21
	v_fma_f32 v24, -v20, v23, v22
	v_fmac_f32_e32 v23, v24, v21
	v_fma_f32 v20, -v20, v23, v22
	v_div_fmas_f32 v20, v20, v21, v23
	v_div_fixup_f32 v17, v20, v17, 1.0
	v_div_scale_f32 v20, s[4:5], v16, v16, 1.0
	v_rcp_f32_e32 v21, v20
	s_nop 0
	v_fma_f32 v22, -v20, v21, 1.0
	v_fmac_f32_e32 v21, v22, v21
	v_div_scale_f32 v22, vcc, 1.0, v16, 1.0
	v_mul_f32_e32 v23, v22, v21
	v_fma_f32 v24, -v20, v23, v22
	v_fmac_f32_e32 v23, v24, v21
	v_fma_f32 v20, -v20, v23, v22
	v_div_fmas_f32 v20, v20, v21, v23
	v_div_fixup_f32 v16, v20, v16, 1.0
	v_pk_mul_f32 v[12:13], v[12:13], v[16:17]
	s_and_b64 vcc, exec, s[38:39]
	s_cbranch_vccnz .LBB0_289
	v_lshlrev_b32_e32 v16, 16, v102
	v_and_b32_e32 v17, 0xffff0000, v102
	v_pk_add_f32 v[10:11], v[10:11], v[16:17]
	v_lshlrev_b32_e32 v16, 16, v103
	v_and_b32_e32 v17, 0xffff0000, v103
	v_pk_add_f32 v[12:13], v[12:13], v[16:17]

; DI float bflo(unsigned u) { return __uint_as_float(u << 16); }
; DI float bfhi(unsigned u) { return __uint_as_float(u & 0xffff0000u); }
; DI float sigmoidf_(float x) { return 1.f / (1.f + __expf(-x)); }
; DI void merge_item(const Params& p, int l, int item, bf16_t* lds) {
;     ...
;       u32x2 g = *(const u32x2*)(RG + (size_t)t * 3072 + br * 1024 + n0 + cl);
;       f32x4 o; o[0] = sigmoidf_(bflo(g.x)) * v[0]; o[1] = sigmoidf_(bfhi(g.x)) * v[1]; o[2] = sigmoidf_(bflo(g.y)) * v[2]; o[3] = sigmoidf_(bfhi(g.y)) * v[3];
;       if (br > 0) { u32x2 pm = mg[mi][ni]; o[0] += bflo(pm.x); o[1] += bfhi(pm.x); o[2] += bflo(pm.y); o[3] += bfhi(pm.y); }
.LBB0_291:
	s_waitcnt vmcnt(0)
	v_permlane16_swap_b32_e32 v202, v204
	v_permlane16_swap_b32_e32 v203, v205
	s_nop 1
	v_mov_b32_e32 v10, v202
	v_mov_b32_e32 v11, v203
	v_lshlrev_b32_e32 v12, 16, v10
	v_and_b32_e32 v10, 0xffff0000, v10
	v_mul_f32_e32 v12, 0xbfb8aa3b, v12
	v_mul_f32_e32 v10, 0xbfb8aa3b, v10
	v_exp_f32_e32 v12, v12
	v_exp_f32_e32 v13, v10
	s_nop 0
	v_pk_add_f32 v[12:13], v[12:13], 1.0 op_sel_hi:[1,0]
	s_nop 0
	v_div_scale_f32 v10, s[4:5], v13, v13, 1.0
	v_rcp_f32_e32 v16, v10
	s_nop 0
	v_fma_f32 v17, -v10, v16, 1.0
	v_fmac_f32_e32 v16, v17, v16
	v_div_scale_f32 v17, vcc, 1.0, v13, 1.0
	v_mul_f32_e32 v20, v17, v16
	v_fma_f32 v21, -v10, v20, v17
	v_fmac_f32_e32 v20, v21, v16
	v_fma_f32 v10, -v10, v20, v17
	v_div_fmas_f32 v10, v10, v16, v20
	v_div_fixup_f32 v13, v10, v13, 1.0
	v_div_scale_f32 v10, s[4:5], v12, v12, 1.0
	v_rcp_f32_e32 v16, v10
	s_nop 0
	v_fma_f32 v17, -v10, v16, 1.0
	v_fmac_f32_e32 v16, v17, v16
	v_div_scale_f32 v17, vcc, 1.0, v12, 1.0
	v_mul_f32_e32 v20, v17, v16
	v_fma_f32 v21, -v10, v20, v17
	v_fmac_f32_e32 v20, v21, v16
	v_fma_f32 v10, -v10, v20, v17
	v_div_fmas_f32 v10, v10, v16, v20
	v_div_fixup_f32 v12, v10, v12, 1.0
	v_lshlrev_b32_e32 v10, 16, v11
	v_and_b32_e32 v11, 0xffff0000, v11
	v_mul_f32_e32 v10, 0xbfb8aa3b, v10
	v_mul_f32_e32 v11, 0xbfb8aa3b, v11
	v_exp_f32_e32 v10, v10
	v_exp_f32_e32 v11, v11
	v_pk_mul_f32 v[6:7], v[6:7], v[12:13]
	v_pk_add_f32 v[10:11], v[10:11], 1.0 op_sel_hi:[1,0]
	s_nop 0
	v_div_scale_f32 v12, s[4:5], v11, v11, 1.0
	v_rcp_f32_e32 v13, v12
	s_nop 0
	v_fma_f32 v16, -v12, v13, 1.0
	v_fmac_f32_e32 v13, v16, v13
	v_div_scale_f32 v16, vcc, 1.0, v11, 1.0
	v_mul_f32_e32 v17, v16, v13
	v_fma_f32 v20, -v12, v17, v16
	v_fmac_f32_e32 v17, v20, v13
	v_fma_f32 v12, -v12, v17, v16
	v_div_fmas_f32 v12, v12, v13, v17
	v_div_fixup_f32 v11, v12, v11, 1.0
	v_div_scale_f32 v12, s[4:5], v10, v10, 1.0
	v_rcp_f32_e32 v13, v12
	s_nop 0
	v_fma_f32 v16, -v12, v13, 1.0
	v_fmac_f32_e32 v13, v16, v13
	v_div_scale_f32 v16, vcc, 1.0, v10, 1.0
	v_mul_f32_e32 v17, v16, v13
	v_fma_f32 v20, -v12, v17, v16
	v_fmac_f32_e32 v17, v20, v13
	v_fma_f32 v12, -v12, v17, v16
	v_div_fmas_f32 v12, v12, v13, v17
	v_div_fixup_f32 v10, v12, v10, 1.0
	v_pk_mul_f32 v[8:9], v[8:9], v[10:11]
	s_and_b64 vcc, exec, s[38:39]
	s_cbranch_vccnz .LBB0_293
	v_lshlrev_b32_e32 v10, 16, v100
	v_and_b32_e32 v11, 0xffff0000, v100
	v_pk_add_f32 v[6:7], v[6:7], v[10:11]
	v_lshlrev_b32_e32 v10, 16, v101
	v_and_b32_e32 v11, 0xffff0000, v101
	v_pk_add_f32 v[8:9], v[8:9], v[10:11]
